# GEMM K-loop LDS-DMA loads use scalar base + 32-bit lane offset (16 64-bit VALU adds per iteration removed; k-step bases kept in spare SGPR pairs)
# speedup vs baseline: 1.0056x; 1.0056x over previous
; #define PG8_STAGE(bufoff, gbase, voff) do { _Pragma("unroll") for (int _i = 0; _i < 2; ++_i) \
;         __builtin_amdgcn_global_load_lds((const unsigned*)((const char*)(gbase) + (voff)[_i]), (LAS unsigned*)(lds + (bufoff) + ldsw + _i * 8192), 16, 0, 0); } while (0)
; #define PG8_LDA(dst, b, h) do { _Pragma("unroll") for (int m = 0; m < 4; ++m) _Pragma("unroll") for (int k = 0; k < 2; ++k) dst[m][k] = *(const LAS bf16x8*)(lds + PG8_SA(b, h) + aoff + m * 2048 + k * 1024); } while (0)
; #define PG8_LDB(dst, b, h) do { _Pragma("unroll") for (int n = 0; n < 2; ++n) _Pragma("unroll") for (int k = 0; k < 2; ++k) dst[n][k] = *(const LAS bf16x8*)(lds + PG8_SB(b, h) + boff + n * 2048 + k * 1024); } while (0)
; #define PG8_MMA(ai, bj, At, Bt) do { __builtin_amdgcn_s_setprio(1); _Pragma("unroll") for (int m = 0; m < 4; ++m) _Pragma("unroll") for (int n = 0; n < 2; ++n) _Pragma("unroll") for (int k = 0; k < 2; ++k) \
;         acc[ai][bj][m][n] = __builtin_amdgcn_mfma_f32_16x16x32_bf16(Bt[n][k], At[m][k], acc[ai][bj][m][n], 0, 0, 0); __builtin_amdgcn_s_setprio(0); } while (0)
; #define PG8_WAIT_V(n) asm volatile("s_waitcnt vmcnt(" #n ")" ::: "memory")
; #define PG8_BAR __builtin_amdgcn_s_barrier()
; template <class F>
; DI void gemm_phase(const int tid, LAS unsigned char* lds, const bf16_t* Ap, int lda, const bf16_t* Bp, int ldb, int M, int N, int K, int G, int c, bool direct, const F& E) {
;     ...
;         for (int t = 0; t < nt; t += 2) {
;             const bool last = (t == nt - 2);
;             const char* a1 = cA + (size_t)(t + 1) * kstep;
;             const char* a2 = last ? nA : cA + (size_t)(t + 2) * kstep; const char* b2 = last ? nB : cB + (size_t)(t + 2) * kstep;
;             const char* a3 = a2 + kstep; const char* b3 = b2 + kstep;
;             PG8_LDB(B0, 0, 0); PG8_SCHED; PG8_LDA(At, 0, 0); PG8_STAGE(PG8_SA(1, 1), a1 + hsA, voffA);
;             PG8_WAIT_L(8); PG8_BAR; PG8_WAIT_L(0); PG8_MMA(0, 0, At, B0); PG8_BAR; PG8_SCHED;
;             PG8_LDB(B1, 0, 1); PG8_STAGE(PG8_SB(0, 0), b2, voffB);
;             PG8_BAR; PG8_WAIT_L(0); PG8_MMA(0, 1, At, B1); PG8_BAR;
;             PG8_LDA(At, 0, 1); PG8_STAGE(PG8_SA(0, 0), a2, voffA);
;             PG8_BAR; PG8_WAIT_L(0); PG8_MMA(1, 0, At, B0); PG8_BAR; PG8_SCHED;
;             PG8_STAGE(PG8_SB(0, 1), b2 + hsB, voffB);
;             PG8_WAIT_V(6); PG8_BAR; PG8_MMA(1, 1, At, B1); PG8_BAR;
.LBB0_657:
	s_add_i32 s81, s76, 2
	s_add_u32 s78, s74, 0x80
	s_addc_u32 s77, s75, 0
	s_add_i32 s82, 0, 0x10000
	v_add_u32_e32 v140, s82, v189
	ds_read_b128 v[128:131], v140
	ds_read_b128 v[132:135], v140 offset:1024
	ds_read_b128 v[136:139], v140 offset:2048
	ds_read_b128 v[140:143], v140 offset:3072
	s_cmp_eq_u32 s67, s76
	s_cselect_b32 s76, s0, s78
	s_cselect_b32 s77, s1, s77
	s_cselect_b32 s79, s5, s80
	s_cselect_b32 s78, s4, s71
	s_add_u32 s98, s78, 0x80
	s_addc_u32 s99, s79, 0
	s_add_u32 s100, s76, 0x80
	s_addc_u32 s101, s77, 0
	s_add_i32 m0, s28, 0xc000
	ds_read_b128 v[144:147], v197
	ds_read_b128 v[148:151], v197 offset:1024
	ds_read_b128 v[152:155], v197 offset:2048
	ds_read_b128 v[156:159], v197 offset:3072
	ds_read_b128 v[160:163], v197 offset:4096
	ds_read_b128 v[164:167], v197 offset:5120
	ds_read_b128 v[168:171], v197 offset:6144
	ds_read_b128 v[172:175], v197 offset:7168
	global_load_lds_dwordx4 v204, s[74:75]
	s_add_i32 m0, s28, 0xe000
	s_nop 0
	global_load_lds_dwordx4 v206, s[74:75]
	s_waitcnt lgkmcnt(8)
	s_barrier
	s_waitcnt lgkmcnt(0)
	s_waitcnt lgkmcnt(0)
	v_mfma_f32_16x16x32_bf16 v[124:127], v[128:131], v[144:147], v[124:127]
	v_mfma_f32_16x16x32_bf16 v[120:123], v[136:139], v[144:147], v[120:123]
	v_mfma_f32_16x16x32_bf16 v[116:119], v[128:131], v[152:155], v[116:119]
	v_mfma_f32_16x16x32_bf16 v[104:107], v[136:139], v[152:155], v[104:107]
	v_mfma_f32_16x16x32_bf16 v[100:103], v[128:131], v[160:163], v[100:103]
	v_mfma_f32_16x16x32_bf16 v[88:91], v[136:139], v[160:163], v[88:91]
	v_mfma_f32_16x16x32_bf16 v[84:87], v[128:131], v[168:171], v[84:87]
	v_mfma_f32_16x16x32_bf16 v[72:75], v[136:139], v[168:171], v[72:75]
	v_mfma_f32_16x16x32_bf16 v[124:127], v[132:135], v[148:151], v[124:127]
	v_mfma_f32_16x16x32_bf16 v[120:123], v[140:143], v[148:151], v[120:123]
	v_mfma_f32_16x16x32_bf16 v[116:119], v[132:135], v[156:159], v[116:119]
	v_mfma_f32_16x16x32_bf16 v[104:107], v[140:143], v[156:159], v[104:107]
	v_mfma_f32_16x16x32_bf16 v[100:103], v[132:135], v[164:167], v[100:103]
	v_mfma_f32_16x16x32_bf16 v[88:91], v[140:143], v[164:167], v[88:91]
	v_mfma_f32_16x16x32_bf16 v[84:87], v[132:135], v[172:175], v[84:87]
	v_mfma_f32_16x16x32_bf16 v[72:75], v[140:143], v[172:175], v[72:75]
	s_barrier
	s_add_i32 s82, s82, s27
	v_add_u32_e32 v180, s95, v189
	s_mov_b32 m0, s82
	ds_read_b128 v[208:211], v180
	ds_read_b128 v[212:215], v180 offset:1024
	ds_read_b128 v[216:219], v180 offset:2048
	ds_read_b128 v[220:223], v180 offset:3072
	global_load_lds_dwordx4 v178, s[78:79]
	s_add_i32 m0, s82, 0x2000
	s_nop 0
	global_load_lds_dwordx4 v186, s[78:79]
	s_barrier
	s_waitcnt lgkmcnt(0)
	s_waitcnt lgkmcnt(0)
	v_mfma_f32_16x16x32_bf16 v[112:115], v[208:211], v[144:147], v[112:115]
	v_mfma_f32_16x16x32_bf16 v[108:111], v[216:219], v[144:147], v[108:111]
	v_mfma_f32_16x16x32_bf16 v[96:99], v[208:211], v[152:155], v[96:99]
	v_mfma_f32_16x16x32_bf16 v[92:95], v[216:219], v[152:155], v[92:95]
	v_mfma_f32_16x16x32_bf16 v[80:83], v[208:211], v[160:163], v[80:83]
	v_mfma_f32_16x16x32_bf16 v[76:79], v[216:219], v[160:163], v[76:79]
	v_mfma_f32_16x16x32_bf16 v[68:71], v[208:211], v[168:171], v[68:71]
	v_mfma_f32_16x16x32_bf16 v[64:67], v[216:219], v[168:171], v[64:67]
	v_mfma_f32_16x16x32_bf16 v[112:115], v[212:215], v[148:151], v[112:115]
	v_mfma_f32_16x16x32_bf16 v[108:111], v[220:223], v[148:151], v[108:111]
	v_mfma_f32_16x16x32_bf16 v[96:99], v[212:215], v[156:159], v[96:99]
	v_mfma_f32_16x16x32_bf16 v[92:95], v[220:223], v[156:159], v[92:95]
	v_mfma_f32_16x16x32_bf16 v[80:83], v[212:215], v[164:167], v[80:83]
	v_mfma_f32_16x16x32_bf16 v[76:79], v[220:223], v[164:167], v[76:79]
	v_mfma_f32_16x16x32_bf16 v[68:71], v[212:215], v[172:175], v[68:71]
	v_mfma_f32_16x16x32_bf16 v[64:67], v[220:223], v[172:175], v[64:67]
	s_mov_b32 m0, s28
	s_barrier
	ds_read_b128 v[144:147], v197 offset:16384
	ds_read_b128 v[148:151], v197 offset:17408
	ds_read_b128 v[152:155], v197 offset:18432
	ds_read_b128 v[156:159], v197 offset:19456
	ds_read_b128 v[160:163], v197 offset:20480
	ds_read_b128 v[164:167], v197 offset:21504
	ds_read_b128 v[168:171], v197 offset:22528
	ds_read_b128 v[172:175], v197 offset:23552
	global_load_lds_dwordx4 v176, s[76:77]
	s_mov_b32 m0, s34
	s_nop 0
	global_load_lds_dwordx4 v184, s[76:77]
	s_barrier
	s_waitcnt lgkmcnt(0)
	s_waitcnt lgkmcnt(0)
	v_mfma_f32_16x16x32_bf16 v[60:63], v[128:131], v[144:147], v[60:63]
	v_mfma_f32_16x16x32_bf16 v[56:59], v[136:139], v[144:147], v[56:59]
	v_mfma_f32_16x16x32_bf16 v[52:55], v[128:131], v[152:155], v[52:55]
	v_mfma_f32_16x16x32_bf16 v[40:43], v[136:139], v[152:155], v[40:43]
	v_mfma_f32_16x16x32_bf16 v[36:39], v[128:131], v[160:163], v[36:39]
	v_mfma_f32_16x16x32_bf16 v[16:19], v[136:139], v[160:163], v[16:19]
	v_mfma_f32_16x16x32_bf16 v[12:15], v[128:131], v[168:171], v[12:15]
	v_mfma_f32_16x16x32_bf16 v[0:3], v[136:139], v[168:171], v[0:3]
	v_mfma_f32_16x16x32_bf16 v[60:63], v[132:135], v[148:151], v[60:63]
	v_mfma_f32_16x16x32_bf16 v[56:59], v[140:143], v[148:151], v[56:59]
	v_mfma_f32_16x16x32_bf16 v[52:55], v[132:135], v[156:159], v[52:55]
	v_mfma_f32_16x16x32_bf16 v[40:43], v[140:143], v[156:159], v[40:43]
	v_mfma_f32_16x16x32_bf16 v[36:39], v[132:135], v[164:167], v[36:39]
	v_mfma_f32_16x16x32_bf16 v[16:19], v[140:143], v[164:167], v[16:19]
	v_mfma_f32_16x16x32_bf16 v[12:15], v[132:135], v[172:175], v[12:15]
	v_mfma_f32_16x16x32_bf16 v[0:3], v[140:143], v[172:175], v[0:3]
	s_barrier
	s_add_u32 s78, s78, s46
	s_addc_u32 s79, s79, 0
	s_add_u32 vcc_lo, s78, 0x80
	s_addc_u32 vcc_hi, s79, 0
	s_add_i32 s82, s95, s27
	s_mov_b32 m0, s82
	s_nop 0
	global_load_lds_dwordx4 v178, s[78:79]
	s_add_i32 m0, s82, 0x2000
	s_nop 0
	global_load_lds_dwordx4 v186, s[78:79]
	s_waitcnt vmcnt(6)
	s_barrier
; #define PG8_STAGE(bufoff, gbase, voff) do { _Pragma("unroll") for (int _i = 0; _i < 2; ++_i) \
;         __builtin_amdgcn_global_load_lds((const unsigned*)((const char*)(gbase) + (voff)[_i]), (LAS unsigned*)(lds + (bufoff) + ldsw + _i * 8192), 16, 0, 0); } while (0)
; #define PG8_LDA(dst, b, h) do { _Pragma("unroll") for (int m = 0; m < 4; ++m) _Pragma("unroll") for (int k = 0; k < 2; ++k) dst[m][k] = *(const LAS bf16x8*)(lds + PG8_SA(b, h) + aoff + m * 2048 + k * 1024); } while (0)
; #define PG8_LDB(dst, b, h) do { _Pragma("unroll") for (int n = 0; n < 2; ++n) _Pragma("unroll") for (int k = 0; k < 2; ++k) dst[n][k] = *(const LAS bf16x8*)(lds + PG8_SB(b, h) + boff + n * 2048 + k * 1024); } while (0)
; #define PG8_MMA(ai, bj, At, Bt) do { __builtin_amdgcn_s_setprio(1); _Pragma("unroll") for (int m = 0; m < 4; ++m) _Pragma("unroll") for (int n = 0; n < 2; ++n) _Pragma("unroll") for (int k = 0; k < 2; ++k) \
;         acc[ai][bj][m][n] = __builtin_amdgcn_mfma_f32_16x16x32_bf16(Bt[n][k], At[m][k], acc[ai][bj][m][n], 0, 0, 0); __builtin_amdgcn_s_setprio(0); } while (0)
; #define PG8_WAIT_V(n) asm volatile("s_waitcnt vmcnt(" #n ")" ::: "memory")
; #define PG8_WAIT_L(n) asm volatile("s_waitcnt lgkmcnt(" #n ")" ::: "memory")
; #define PG8_BAR __builtin_amdgcn_s_barrier()
; #define PG8_SCHED __builtin_amdgcn_sched_barrier(0)
; template <class F>
; DI void gemm_phase(const int tid, LAS unsigned char* lds, const bf16_t* Ap, int lda, const bf16_t* Bp, int ldb, int M, int N, int K, int G, int c, bool direct, const F& E) {
;     ...
;             PG8_BAR; PG8_WAIT_L(0); PG8_MMA(1, 0, At, B0); PG8_BAR; PG8_SCHED;
;             PG8_STAGE(PG8_SB(0, 1), b2 + hsB, voffB);
;             PG8_WAIT_V(6); PG8_BAR; PG8_MMA(1, 1, At, B1); PG8_BAR;
;             PG8_LDB(B0, 1, 0); PG8_SCHED; PG8_LDA(At, 1, 0); PG8_STAGE(PG8_SA(0, 1), a2 + hsA, voffA);
;             PG8_WAIT_L(8); PG8_BAR; PG8_WAIT_L(0); PG8_MMA(0, 0, At, B0); PG8_BAR; PG8_SCHED;
;             PG8_LDB(B1, 1, 1); PG8_STAGE(PG8_SB(1, 0), b3, voffB);
;             PG8_BAR; PG8_WAIT_L(0); PG8_MMA(0, 1, At, B1); PG8_BAR;
;             PG8_LDA(At, 1, 1); PG8_STAGE(PG8_SA(1, 0), a3, voffA);
;             PG8_BAR; PG8_WAIT_L(0); PG8_MMA(1, 0, At, B0); PG8_BAR; PG8_SCHED;
	v_mfma_f32_16x16x32_bf16 v[48:51], v[208:211], v[144:147], v[48:51]
	v_mfma_f32_16x16x32_bf16 v[44:47], v[216:219], v[144:147], v[44:47]
	v_mfma_f32_16x16x32_bf16 v[24:27], v[208:211], v[152:155], v[24:27]
	v_mfma_f32_16x16x32_bf16 v[20:23], v[216:219], v[152:155], v[20:23]
	v_mfma_f32_16x16x32_bf16 v[28:31], v[208:211], v[160:163], v[28:31]
	v_mfma_f32_16x16x32_bf16 v[32:35], v[216:219], v[160:163], v[32:35]
	v_mfma_f32_16x16x32_bf16 v[8:11], v[208:211], v[168:171], v[8:11]
	v_mfma_f32_16x16x32_bf16 v[4:7], v[216:219], v[168:171], v[4:7]
	v_mfma_f32_16x16x32_bf16 v[48:51], v[212:215], v[148:151], v[48:51]
	v_mfma_f32_16x16x32_bf16 v[44:47], v[220:223], v[148:151], v[44:47]
	v_mfma_f32_16x16x32_bf16 v[24:27], v[212:215], v[156:159], v[24:27]
	v_mfma_f32_16x16x32_bf16 v[20:23], v[220:223], v[156:159], v[20:23]
	v_mfma_f32_16x16x32_bf16 v[28:31], v[212:215], v[164:167], v[28:31]
	v_mfma_f32_16x16x32_bf16 v[32:35], v[220:223], v[164:167], v[32:35]
	v_mfma_f32_16x16x32_bf16 v[8:11], v[212:215], v[172:175], v[8:11]
	v_mfma_f32_16x16x32_bf16 v[4:7], v[220:223], v[172:175], v[4:7]
	s_add_i32 s78, 0, 0x18000
	v_add_u32_e32 v140, s78, v189
	s_barrier
	ds_read_b128 v[128:131], v140
	ds_read_b128 v[132:135], v140 offset:1024
	ds_read_b128 v[136:139], v140 offset:2048
	ds_read_b128 v[140:143], v140 offset:3072
	s_add_u32 s76, s76, s24
	s_addc_u32 s77, s77, 0
	s_mov_b32 m0, s60
	ds_read_b128 v[144:147], v197 offset:32768
	ds_read_b128 v[148:151], v197 offset:33792
	ds_read_b128 v[152:155], v197 offset:34816
	ds_read_b128 v[156:159], v197 offset:35840
	ds_read_b128 v[160:163], v197 offset:36864
	ds_read_b128 v[164:167], v197 offset:37888
	ds_read_b128 v[168:171], v197 offset:38912
	ds_read_b128 v[172:175], v197 offset:39936
	global_load_lds_dwordx4 v176, s[76:77]
	s_mov_b32 m0, s61
	s_nop 0
	global_load_lds_dwordx4 v184, s[76:77]
	s_waitcnt lgkmcnt(8)
	s_barrier
	s_waitcnt lgkmcnt(0)
	s_waitcnt lgkmcnt(0)
	v_mfma_f32_16x16x32_bf16 v[124:127], v[128:131], v[144:147], v[124:127]
	v_mfma_f32_16x16x32_bf16 v[120:123], v[136:139], v[144:147], v[120:123]
	v_mfma_f32_16x16x32_bf16 v[116:119], v[128:131], v[152:155], v[116:119]
	v_mfma_f32_16x16x32_bf16 v[104:107], v[136:139], v[152:155], v[104:107]
	v_mfma_f32_16x16x32_bf16 v[100:103], v[128:131], v[160:163], v[100:103]
	v_mfma_f32_16x16x32_bf16 v[88:91], v[136:139], v[160:163], v[88:91]
	v_mfma_f32_16x16x32_bf16 v[84:87], v[128:131], v[168:171], v[84:87]
	v_mfma_f32_16x16x32_bf16 v[72:75], v[136:139], v[168:171], v[72:75]
	v_mfma_f32_16x16x32_bf16 v[124:127], v[132:135], v[148:151], v[124:127]
	v_mfma_f32_16x16x32_bf16 v[120:123], v[140:143], v[148:151], v[120:123]
	v_mfma_f32_16x16x32_bf16 v[116:119], v[132:135], v[156:159], v[116:119]
	v_mfma_f32_16x16x32_bf16 v[104:107], v[140:143], v[156:159], v[104:107]
	v_mfma_f32_16x16x32_bf16 v[100:103], v[132:135], v[164:167], v[100:103]
	v_mfma_f32_16x16x32_bf16 v[88:91], v[140:143], v[164:167], v[88:91]
	v_mfma_f32_16x16x32_bf16 v[84:87], v[132:135], v[172:175], v[84:87]
	v_mfma_f32_16x16x32_bf16 v[72:75], v[140:143], v[172:175], v[72:75]
	s_barrier
	s_add_i32 s76, 0, 0x1c000
	s_add_i32 s77, s78, s27
	v_add_u32_e32 v180, s76, v189
	s_mov_b32 m0, s77
	ds_read_b128 v[208:211], v180
	ds_read_b128 v[212:215], v180 offset:1024
	ds_read_b128 v[216:219], v180 offset:2048
	ds_read_b128 v[220:223], v180 offset:3072
	global_load_lds_dwordx4 v178, s[98:99]
	s_add_i32 m0, s77, 0x2000
	s_nop 0
	global_load_lds_dwordx4 v186, s[98:99]
	s_barrier
	s_waitcnt lgkmcnt(0)
	s_waitcnt lgkmcnt(0)
	v_mfma_f32_16x16x32_bf16 v[112:115], v[208:211], v[144:147], v[112:115]
	v_mfma_f32_16x16x32_bf16 v[108:111], v[216:219], v[144:147], v[108:111]
	v_mfma_f32_16x16x32_bf16 v[96:99], v[208:211], v[152:155], v[96:99]
	v_mfma_f32_16x16x32_bf16 v[92:95], v[216:219], v[152:155], v[92:95]
	v_mfma_f32_16x16x32_bf16 v[80:83], v[208:211], v[160:163], v[80:83]
	v_mfma_f32_16x16x32_bf16 v[76:79], v[216:219], v[160:163], v[76:79]
	v_mfma_f32_16x16x32_bf16 v[68:71], v[208:211], v[168:171], v[68:71]
	v_mfma_f32_16x16x32_bf16 v[64:67], v[216:219], v[168:171], v[64:67]
	v_mfma_f32_16x16x32_bf16 v[112:115], v[212:215], v[148:151], v[112:115]
	v_mfma_f32_16x16x32_bf16 v[108:111], v[220:223], v[148:151], v[108:111]
	v_mfma_f32_16x16x32_bf16 v[96:99], v[212:215], v[156:159], v[96:99]
	v_mfma_f32_16x16x32_bf16 v[92:95], v[220:223], v[156:159], v[92:95]
	v_mfma_f32_16x16x32_bf16 v[80:83], v[212:215], v[164:167], v[80:83]
	v_mfma_f32_16x16x32_bf16 v[76:79], v[220:223], v[164:167], v[76:79]
	v_mfma_f32_16x16x32_bf16 v[68:71], v[212:215], v[172:175], v[68:71]
	v_mfma_f32_16x16x32_bf16 v[64:67], v[220:223], v[172:175], v[64:67]
	s_mov_b32 m0, s62
	s_barrier
	ds_read_b128 v[144:147], v197 offset:49152
	ds_read_b128 v[148:151], v197 offset:50176
	ds_read_b128 v[152:155], v197 offset:51200
	ds_read_b128 v[156:159], v197 offset:52224
	ds_read_b128 v[160:163], v197 offset:53248
	ds_read_b128 v[164:167], v197 offset:54272
	ds_read_b128 v[168:171], v197 offset:55296
	ds_read_b128 v[172:175], v197 offset:56320
	global_load_lds_dwordx4 v176, s[100:101]
	s_mov_b32 m0, s63
	s_nop 0
	global_load_lds_dwordx4 v184, s[100:101]
	s_barrier
; #define PG8_STAGE(bufoff, gbase, voff) do { _Pragma("unroll") for (int _i = 0; _i < 2; ++_i) \
;         __builtin_amdgcn_global_load_lds((const unsigned*)((const char*)(gbase) + (voff)[_i]), (LAS unsigned*)(lds + (bufoff) + ldsw + _i * 8192), 16, 0, 0); } while (0)
; #define PG8_MMA(ai, bj, At, Bt) do { __builtin_amdgcn_s_setprio(1); _Pragma("unroll") for (int m = 0; m < 4; ++m) _Pragma("unroll") for (int n = 0; n < 2; ++n) _Pragma("unroll") for (int k = 0; k < 2; ++k) \
;         acc[ai][bj][m][n] = __builtin_amdgcn_mfma_f32_16x16x32_bf16(Bt[n][k], At[m][k], acc[ai][bj][m][n], 0, 0, 0); __builtin_amdgcn_s_setprio(0); } while (0)
; #define PG8_WAIT_V(n) asm volatile("s_waitcnt vmcnt(" #n ")" ::: "memory")
; #define PG8_WAIT_L(n) asm volatile("s_waitcnt lgkmcnt(" #n ")" ::: "memory")
; #define PG8_BAR __builtin_amdgcn_s_barrier()
; #define PG8_SCHED __builtin_amdgcn_sched_barrier(0)
; template <class F>
; DI void gemm_phase(const int tid, LAS unsigned char* lds, const bf16_t* Ap, int lda, const bf16_t* Bp, int ldb, int M, int N, int K, int G, int c, bool direct, const F& E) {
;     ...
;             PG8_BAR; PG8_WAIT_L(0); PG8_MMA(1, 0, At, B0); PG8_BAR; PG8_SCHED;
;             PG8_STAGE(PG8_SB(1, 1), b3 + hsB, voffB);
;             PG8_WAIT_V(6); PG8_BAR; PG8_MMA(1, 1, At, B1); PG8_BAR;
;         }
;         if (E.kind == 7  ) E.fused(acc, cur.pm, cur.pn, wr, wc, fr, fq);
; DI void Epi::fused(const f32x4 (&acc)[2][2][4][2], int pm, int pn, int wr, int wc, int fr, int fq) const {
;     ...
;         const int ncol = pn * 256 + bj * 128 + wc * 32 + 8 * fq, j0 = (ncol >> 3) * 4;
;         const f32x4 wa0 = *(const f32x4*)(E.cf0 + j0), wa1 = *(const f32x4*)(E.cf0 + FF2 + j0), wa2 = *(const f32x4*)(E.cf0 + 2 * FF2 + j0);
;         const f32x4 wb0 = *(const f32x4*)(E.cf0 + FFH + j0), wb1 = *(const f32x4*)(E.cf0 + FF2 + FFH + j0), wb2 = *(const f32x4*)(E.cf0 + 2 * FF2 + FFH + j0);
;         const f32x4 ba = *(const f32x4*)(E.cf1 + j0), bb = *(const f32x4*)(E.cf1 + FFH + j0);
	s_waitcnt lgkmcnt(0)
	s_waitcnt lgkmcnt(0)
	v_mfma_f32_16x16x32_bf16 v[60:63], v[128:131], v[144:147], v[60:63]
	v_mfma_f32_16x16x32_bf16 v[56:59], v[136:139], v[144:147], v[56:59]
	v_mfma_f32_16x16x32_bf16 v[52:55], v[128:131], v[152:155], v[52:55]
	v_mfma_f32_16x16x32_bf16 v[40:43], v[136:139], v[152:155], v[40:43]
	v_mfma_f32_16x16x32_bf16 v[36:39], v[128:131], v[160:163], v[36:39]
	v_mfma_f32_16x16x32_bf16 v[16:19], v[136:139], v[160:163], v[16:19]
	v_mfma_f32_16x16x32_bf16 v[12:15], v[128:131], v[168:171], v[12:15]
	v_mfma_f32_16x16x32_bf16 v[0:3], v[136:139], v[168:171], v[0:3]
	v_mfma_f32_16x16x32_bf16 v[60:63], v[132:135], v[148:151], v[60:63]
	v_mfma_f32_16x16x32_bf16 v[56:59], v[140:143], v[148:151], v[56:59]
	v_mfma_f32_16x16x32_bf16 v[52:55], v[132:135], v[156:159], v[52:55]
	v_mfma_f32_16x16x32_bf16 v[40:43], v[140:143], v[156:159], v[40:43]
	v_mfma_f32_16x16x32_bf16 v[36:39], v[132:135], v[164:167], v[36:39]
	v_mfma_f32_16x16x32_bf16 v[16:19], v[140:143], v[164:167], v[16:19]
	v_mfma_f32_16x16x32_bf16 v[12:15], v[132:135], v[172:175], v[12:15]
	v_mfma_f32_16x16x32_bf16 v[0:3], v[140:143], v[172:175], v[0:3]
	s_barrier
	s_add_i32 s76, s76, s27
	s_mov_b32 m0, s76
	s_nop 0
	global_load_lds_dwordx4 v178, vcc
	s_add_i32 m0, s76, 0x2000
	s_nop 0
	global_load_lds_dwordx4 v186, vcc
	s_waitcnt vmcnt(6)
	s_barrier
	v_mfma_f32_16x16x32_bf16 v[48:51], v[208:211], v[144:147], v[48:51]
	v_mfma_f32_16x16x32_bf16 v[44:47], v[216:219], v[144:147], v[44:47]
	v_mfma_f32_16x16x32_bf16 v[24:27], v[208:211], v[152:155], v[24:27]
	v_mfma_f32_16x16x32_bf16 v[20:23], v[216:219], v[152:155], v[20:23]
	v_mfma_f32_16x16x32_bf16 v[28:31], v[208:211], v[160:163], v[28:31]
	v_mfma_f32_16x16x32_bf16 v[32:35], v[216:219], v[160:163], v[32:35]
	v_mfma_f32_16x16x32_bf16 v[8:11], v[208:211], v[168:171], v[8:11]
	v_mfma_f32_16x16x32_bf16 v[4:7], v[216:219], v[168:171], v[4:7]
	v_mfma_f32_16x16x32_bf16 v[48:51], v[212:215], v[148:151], v[48:51]
	v_mfma_f32_16x16x32_bf16 v[44:47], v[220:223], v[148:151], v[44:47]
	v_mfma_f32_16x16x32_bf16 v[24:27], v[212:215], v[156:159], v[24:27]
	v_mfma_f32_16x16x32_bf16 v[20:23], v[220:223], v[156:159], v[20:23]
	v_mfma_f32_16x16x32_bf16 v[28:31], v[212:215], v[164:167], v[28:31]
	v_mfma_f32_16x16x32_bf16 v[32:35], v[220:223], v[164:167], v[32:35]
	v_mfma_f32_16x16x32_bf16 v[8:11], v[212:215], v[172:175], v[8:11]
	v_mfma_f32_16x16x32_bf16 v[4:7], v[220:223], v[172:175], v[4:7]
	s_add_u32 s74, s74, 0x100
	s_addc_u32 s75, s75, 0
	s_add_u32 s71, s71, 0x100
	s_addc_u32 s80, s80, 0
	s_cmp_ge_u32 s81, s26
	s_mov_b32 s76, s81
	s_barrier
	s_cbranch_scc0 .LBB0_657
	s_mov_b64 s[76:77], -1
	s_mov_b64 s[74:75], 0
	s_cmp_lt_i32 s92, 3
	s_mov_b64 s[78:79], 0
	s_cbranch_scc1 .LBB0_688
	s_cmp_gt_i32 s92, 6
	s_mov_b64 s[78:79], -1
	s_cbranch_scc0 .LBB0_685
	v_lshl_or_b32 v240, s70, 8, v194
	v_mov_b32_e32 v241, 0
	s_lshl_b32 s71, s36, 8
	v_readlane_b32 s76, v255, 16
	s_nop 3
	s_add_i32 s71, s71, s76
	v_or_b32_e32 v199, s71, v188
	v_lshlrev_b32_e32 v238, 1, v240
	v_mov_b32_e32 v239, 0
	v_lshl_add_u64 v[136:137], s[22:23], 0, v[238:239]
	global_load_dwordx4 v[136:139], v[136:137], off
	v_readlane_b32 s76, v254, 54
	v_readlane_b32 s77, v254, 55
	s_nop 1
	v_lshl_add_u64 v[140:141], s[76:77], 0, v[238:239]
	global_load_dwordx4 v[140:143], v[140:141], off
	v_readlane_b32 s76, v254, 56
	v_readlane_b32 s77, v254, 57
	s_nop 1
	v_lshl_add_u64 v[152:153], s[76:77], 0, v[238:239]
	global_load_dwordx4 v[152:155], v[152:153], off
	v_readlane_b32 s76, v255, 4
	v_readlane_b32 s77, v255, 5
	s_nop 1
	v_lshl_add_u64 v[128:129], s[76:77], 0, v[238:239]
	global_load_dwordx4 v[128:131], v[128:129], off
	v_readlane_b32 s76, v255, 6
	v_readlane_b32 s77, v255, 7
	s_nop 1
	v_lshl_add_u64 v[132:133], s[76:77], 0, v[238:239]
	global_load_dwordx4 v[132:135], v[132:133], off
	v_readlane_b32 s76, v255, 8
	v_readlane_b32 s77, v255, 9
	s_nop 1
	v_lshl_add_u64 v[144:145], s[76:77], 0, v[238:239]
	global_load_dwordx4 v[144:147], v[144:145], off
	v_readlane_b32 s76, v254, 49
	v_readlane_b32 s77, v254, 50
	s_nop 1
	v_lshl_add_u64 v[156:157], s[76:77], 0, v[238:239]
	global_load_dwordx4 v[156:159], v[156:157], off
	v_lshl_add_u64 v[148:149], s[72:73], 0, v[238:239]
	global_load_dwordx4 v[148:151], v[148:149], off
	v_mov_b32_e32 v228, v199
	v_mov_b64_e32 v[224:225], s[12:13]
	s_movk_i32 s80, 0x1600
	v_mad_i64_i32 v[224:225], s[78:79], v228, s80, v[224:225]
	v_mov_b32_e32 v228, v240
	v_mov_b32_e32 v229, 0
	v_lshl_add_u64 v[224:225], v[228:229], 0, v[224:225]
	s_waitcnt vmcnt(0)
; DI float silu_fast(float x) { return x * __builtin_amdgcn_rcpf(1.f + __expf(-x)); }
; template <int CTRL> DI float dppf(float v) { return __builtin_bit_cast(float, __builtin_amdgcn_update_dpp(0, __builtin_bit_cast(int, v), CTRL, 0xf, 0xf, true)); }
; DI void Epi::fused(const f32x4 (&acc)[2][2][4][2], int pm, int pn, int wr, int wc, int fr, int fq) const {
;     ...
;             for (int m = 0; m < 4; ++m) {
;                 const f32x4 ca = acc[ai][bj][m][0], cb = acc[ai][bj][m][1];
;                 const int row = pm * 256 + ai * 128 + wr * 64 + m * 16 + fr;
;                 float o[4];
; #pragma unroll
;                 for (int e = 0; e < 4; ++e) {
;                     const float a1 = dppf<0x111>(ca[e]) + dppf<0x10F>(pa[e]), a2 = dppf<0x112>(ca[e]) + dppf<0x10E>(pa[e]);
;                     const float b1 = dppf<0x111>(cb[e]) + dppf<0x10F>(pb[e]), b2 = dppf<0x112>(cb[e]) + dppf<0x10E>(pb[e]);
;                     const float ya = fmaf(wa0[e], a2, fmaf(wa1[e], a1, fmaf(wa2[e], ca[e], ba[e])));
;                     const float yb = fmaf(wb0[e], b2, fmaf(wb1[e], b1, fmaf(wb2[e], cb[e], bb[e])));
;                     o[e] = silu_fast(ya) * yb; }
;                 if (m > 0 || fr >= 2) { u32x2 w; w.x = pk2(o[0], o[1]); w.y = pk2(o[2], o[3]); *(u32x2*)(E.d0 + (size_t)row * FFH + j0) = w; }
;                 if ((m == 0 && fr < 2) || (m == 3 && fr >= 14)) { float* hb = E.f0 + ((size_t)(row >> 6) * 4 + (m == 0 ? fr : fr - 12)) * FF2 + ncol; *(f32x4*)hb = ca; *(f32x4*)(hb + 4) = cb; }
;                 pa = ca; pb = cb;
	v_fma_f32 v160, v152, v124, v156
	v_fma_f32 v161, v153, v125, v157
	v_fma_f32 v162, v154, v126, v158
	v_fma_f32 v163, v155, v127, v159
	v_fma_f32 v164, v144, v120, v148
	v_fma_f32 v165, v145, v121, v149
	v_fma_f32 v166, v146, v122, v150
	v_fma_f32 v167, v147, v123, v151
	v_fmac_f32_dpp v160, v124, v140 row_shr:1 row_mask:0xf bank_mask:0xf
	v_fmac_f32_dpp v161, v125, v141 row_shr:1 row_mask:0xf bank_mask:0xf
	v_fmac_f32_dpp v162, v126, v142 row_shr:1 row_mask:0xf bank_mask:0xf
	v_fmac_f32_dpp v163, v127, v143 row_shr:1 row_mask:0xf bank_mask:0xf
	v_fmac_f32_dpp v164, v120, v132 row_shr:1 row_mask:0xf bank_mask:0xf
	v_fmac_f32_dpp v165, v121, v133 row_shr:1 row_mask:0xf bank_mask:0xf
	v_fmac_f32_dpp v166, v122, v134 row_shr:1 row_mask:0xf bank_mask:0xf
	v_fmac_f32_dpp v167, v123, v135 row_shr:1 row_mask:0xf bank_mask:0xf
	v_fmac_f32_dpp v160, v124, v136 row_shr:2 row_mask:0xf bank_mask:0xf
	v_fmac_f32_dpp v161, v125, v137 row_shr:2 row_mask:0xf bank_mask:0xf
	v_fmac_f32_dpp v162, v126, v138 row_shr:2 row_mask:0xf bank_mask:0xf
	v_fmac_f32_dpp v163, v127, v139 row_shr:2 row_mask:0xf bank_mask:0xf
	v_fmac_f32_dpp v164, v120, v128 row_shr:2 row_mask:0xf bank_mask:0xf
	v_fmac_f32_dpp v165, v121, v129 row_shr:2 row_mask:0xf bank_mask:0xf
	v_fmac_f32_dpp v166, v122, v130 row_shr:2 row_mask:0xf bank_mask:0xf
	v_fmac_f32_dpp v167, v123, v131 row_shr:2 row_mask:0xf bank_mask:0xf
	v_mul_f32_e32 v168, 0xbfb8aa3b, v160
	v_mul_f32_e32 v169, 0xbfb8aa3b, v161
	v_mul_f32_e32 v170, 0xbfb8aa3b, v162
	v_mul_f32_e32 v171, 0xbfb8aa3b, v163
	v_exp_f32_e32 v168, v168
	v_exp_f32_e32 v169, v169
	v_exp_f32_e32 v170, v170
	v_exp_f32_e32 v171, v171
	v_add_f32_e32 v168, 1.0, v168
	v_add_f32_e32 v169, 1.0, v169
	v_add_f32_e32 v170, 1.0, v170
	v_add_f32_e32 v171, 1.0, v171
	v_rcp_f32_e32 v168, v168
	v_rcp_f32_e32 v169, v169
	v_rcp_f32_e32 v170, v170
	v_rcp_f32_e32 v171, v171
	v_mov_b64_e32 v[174:175], v[224:225]
	v_mul_f32_e32 v160, v160, v168
	v_mul_f32_e32 v161, v161, v169
	v_mul_f32_e32 v162, v162, v170
	v_mul_f32_e32 v163, v163, v171
	v_mul_f32_e32 v160, v164, v160
	v_mul_f32_e32 v161, v165, v161
	v_mul_f32_e32 v162, v166, v162
	v_mul_f32_e32 v163, v167, v163
	v_cvt_pk_bf16_f32 v172, v160, v161
	v_cvt_pk_bf16_f32 v173, v162, v163
	s_and_saveexec_b64 s[76:77], s[38:39]
	global_store_dwordx2 v[174:175], v[172:173], off
	s_or_b64 exec, exec, s[76:77]
	s_ashr_i32 s80, s71, 6
	s_lshl_b32 s80, s80, 2
	v_add_u32_e32 v226, s80, v188
	v_mov_b64_e32 v[174:175], s[8:9]
	s_movk_i32 s80, 0x5800
	v_mad_i64_i32 v[174:175], s[78:79], v226, s80, v[174:175]
	v_lshl_add_u64 v[174:175], v[228:229], 2, v[174:175]
	s_and_saveexec_b64 s[76:77], s[40:41]
	global_store_dwordx4 v[174:175], v[124:127], off
	global_store_dwordx4 v[174:175], v[120:123], off offset:16
	s_or_b64 exec, exec, s[76:77]
	v_fma_f32 v208, v152, v116, v156
	v_fma_f32 v209, v153, v117, v157
	v_fma_f32 v210, v154, v118, v158
	v_fma_f32 v211, v155, v119, v159
	v_fma_f32 v212, v144, v104, v148
	v_fma_f32 v213, v145, v105, v149
	v_fma_f32 v214, v146, v106, v150
	v_fma_f32 v215, v147, v107, v151
	v_fmac_f32_dpp v208, v116, v140 row_shr:1 row_mask:0xf bank_mask:0xf
	v_fmac_f32_dpp v209, v117, v141 row_shr:1 row_mask:0xf bank_mask:0xf
	v_fmac_f32_dpp v210, v118, v142 row_shr:1 row_mask:0xf bank_mask:0xf
	v_fmac_f32_dpp v211, v119, v143 row_shr:1 row_mask:0xf bank_mask:0xf
	v_fmac_f32_dpp v212, v104, v132 row_shr:1 row_mask:0xf bank_mask:0xf
	v_fmac_f32_dpp v213, v105, v133 row_shr:1 row_mask:0xf bank_mask:0xf
	v_fmac_f32_dpp v214, v106, v134 row_shr:1 row_mask:0xf bank_mask:0xf
	v_fmac_f32_dpp v215, v107, v135 row_shr:1 row_mask:0xf bank_mask:0xf
	v_fmac_f32_dpp v208, v124, v140 row_shl:15 row_mask:0xf bank_mask:0xf
	v_fmac_f32_dpp v209, v125, v141 row_shl:15 row_mask:0xf bank_mask:0xf
	v_fmac_f32_dpp v210, v126, v142 row_shl:15 row_mask:0xf bank_mask:0xf
	v_fmac_f32_dpp v211, v127, v143 row_shl:15 row_mask:0xf bank_mask:0xf
	v_fmac_f32_dpp v212, v120, v132 row_shl:15 row_mask:0xf bank_mask:0xf
	v_fmac_f32_dpp v213, v121, v133 row_shl:15 row_mask:0xf bank_mask:0xf
	v_fmac_f32_dpp v214, v122, v134 row_shl:15 row_mask:0xf bank_mask:0xf
	v_fmac_f32_dpp v215, v123, v135 row_shl:15 row_mask:0xf bank_mask:0xf
	v_fmac_f32_dpp v208, v116, v136 row_shr:2 row_mask:0xf bank_mask:0xf
	v_fmac_f32_dpp v209, v117, v137 row_shr:2 row_mask:0xf bank_mask:0xf
	v_fmac_f32_dpp v210, v118, v138 row_shr:2 row_mask:0xf bank_mask:0xf
	v_fmac_f32_dpp v211, v119, v139 row_shr:2 row_mask:0xf bank_mask:0xf
	v_fmac_f32_dpp v212, v104, v128 row_shr:2 row_mask:0xf bank_mask:0xf
	v_fmac_f32_dpp v213, v105, v129 row_shr:2 row_mask:0xf bank_mask:0xf
	v_fmac_f32_dpp v214, v106, v130 row_shr:2 row_mask:0xf bank_mask:0xf
	v_fmac_f32_dpp v215, v107, v131 row_shr:2 row_mask:0xf bank_mask:0xf
	v_fmac_f32_dpp v208, v124, v136 row_shl:14 row_mask:0xf bank_mask:0xf
	v_fmac_f32_dpp v209, v125, v137 row_shl:14 row_mask:0xf bank_mask:0xf
	v_fmac_f32_dpp v210, v126, v138 row_shl:14 row_mask:0xf bank_mask:0xf
	v_fmac_f32_dpp v211, v127, v139 row_shl:14 row_mask:0xf bank_mask:0xf
	v_fmac_f32_dpp v212, v120, v128 row_shl:14 row_mask:0xf bank_mask:0xf
	v_fmac_f32_dpp v213, v121, v129 row_shl:14 row_mask:0xf bank_mask:0xf
	v_fmac_f32_dpp v214, v122, v130 row_shl:14 row_mask:0xf bank_mask:0xf
	v_fmac_f32_dpp v215, v123, v131 row_shl:14 row_mask:0xf bank_mask:0xf
	v_mul_f32_e32 v216, 0xbfb8aa3b, v208
	v_mul_f32_e32 v217, 0xbfb8aa3b, v209
	v_mul_f32_e32 v218, 0xbfb8aa3b, v210
	v_mul_f32_e32 v219, 0xbfb8aa3b, v211
	v_exp_f32_e32 v216, v216
	v_exp_f32_e32 v217, v217
	v_exp_f32_e32 v218, v218
	v_exp_f32_e32 v219, v219
	v_add_f32_e32 v216, 1.0, v216
	v_add_f32_e32 v217, 1.0, v217
; DI float silu_fast(float x) { return x * __builtin_amdgcn_rcpf(1.f + __expf(-x)); }
; template <int CTRL> DI float dppf(float v) { return __builtin_bit_cast(float, __builtin_amdgcn_update_dpp(0, __builtin_bit_cast(int, v), CTRL, 0xf, 0xf, true)); }
; DI void Epi::fused(const f32x4 (&acc)[2][2][4][2], int pm, int pn, int wr, int wc, int fr, int fq) const {
;     ...
;     for (int bj = 0; bj < 2; ++bj) {
;         const int ncol = pn * 256 + bj * 128 + wc * 32 + 8 * fq, j0 = (ncol >> 3) * 4;
;         const f32x4 wa0 = *(const f32x4*)(E.cf0 + j0), wa1 = *(const f32x4*)(E.cf0 + FF2 + j0), wa2 = *(const f32x4*)(E.cf0 + 2 * FF2 + j0);
;         const f32x4 wb0 = *(const f32x4*)(E.cf0 + FFH + j0), wb1 = *(const f32x4*)(E.cf0 + FF2 + FFH + j0), wb2 = *(const f32x4*)(E.cf0 + 2 * FF2 + FFH + j0);
;         const f32x4 ba = *(const f32x4*)(E.cf1 + j0), bb = *(const f32x4*)(E.cf1 + FFH + j0);
; #pragma unroll
;         for (int ai = 0; ai < 2; ++ai) {
;             f32x4 pa = (f32x4){0.f, 0.f, 0.f, 0.f}, pb = pa;
; #pragma unroll
;             for (int m = 0; m < 4; ++m) {
;                 const f32x4 ca = acc[ai][bj][m][0], cb = acc[ai][bj][m][1];
;                 const int row = pm * 256 + ai * 128 + wr * 64 + m * 16 + fr;
;                 float o[4];
; #pragma unroll
;                 for (int e = 0; e < 4; ++e) {
;                     const float a1 = dppf<0x111>(ca[e]) + dppf<0x10F>(pa[e]), a2 = dppf<0x112>(ca[e]) + dppf<0x10E>(pa[e]);
;                     const float b1 = dppf<0x111>(cb[e]) + dppf<0x10F>(pb[e]), b2 = dppf<0x112>(cb[e]) + dppf<0x10E>(pb[e]);
;                     const float ya = fmaf(wa0[e], a2, fmaf(wa1[e], a1, fmaf(wa2[e], ca[e], ba[e])));
;                     const float yb = fmaf(wb0[e], b2, fmaf(wb1[e], b1, fmaf(wb2[e], cb[e], bb[e])));
;                     o[e] = silu_fast(ya) * yb; }
;                 if (m > 0 || fr >= 2) { u32x2 w; w.x = pk2(o[0], o[1]); w.y = pk2(o[2], o[3]); *(u32x2*)(E.d0 + (size_t)row * FFH + j0) = w; }
;                 if ((m == 0 && fr < 2) || (m == 3 && fr >= 14)) { float* hb = E.f0 + ((size_t)(row >> 6) * 4 + (m == 0 ? fr : fr - 12)) * FF2 + ncol; *(f32x4*)hb = ca; *(f32x4*)(hb + 4) = cb; }
;                 pa = ca; pb = cb;
	v_add_f32_e32 v218, 1.0, v218
	v_add_f32_e32 v219, 1.0, v219
	v_rcp_f32_e32 v216, v216
	v_rcp_f32_e32 v217, v217
	v_rcp_f32_e32 v218, v218
	v_rcp_f32_e32 v219, v219
	s_mov_b32 s80, 0x16000
	s_mov_b32 s81, 0
	v_lshl_add_u64 v[222:223], v[224:225], 0, s[80:81]
	v_mul_f32_e32 v208, v208, v216
	v_mul_f32_e32 v209, v209, v217
	v_mul_f32_e32 v210, v210, v218
	v_mul_f32_e32 v211, v211, v219
	v_mul_f32_e32 v208, v212, v208
	v_mul_f32_e32 v209, v213, v209
	v_mul_f32_e32 v210, v214, v210
	v_mul_f32_e32 v211, v215, v211
	v_cvt_pk_bf16_f32 v220, v208, v209
	v_cvt_pk_bf16_f32 v221, v210, v211
	global_store_dwordx2 v[222:223], v[220:221], off
	v_fma_f32 v160, v152, v100, v156
	v_fma_f32 v161, v153, v101, v157
	v_fma_f32 v162, v154, v102, v158
	v_fma_f32 v163, v155, v103, v159
	v_fma_f32 v164, v144, v88, v148
	v_fma_f32 v165, v145, v89, v149
	v_fma_f32 v166, v146, v90, v150
	v_fma_f32 v167, v147, v91, v151
	v_fmac_f32_dpp v160, v100, v140 row_shr:1 row_mask:0xf bank_mask:0xf
	v_fmac_f32_dpp v161, v101, v141 row_shr:1 row_mask:0xf bank_mask:0xf
	v_fmac_f32_dpp v162, v102, v142 row_shr:1 row_mask:0xf bank_mask:0xf
	v_fmac_f32_dpp v163, v103, v143 row_shr:1 row_mask:0xf bank_mask:0xf
	v_fmac_f32_dpp v164, v88, v132 row_shr:1 row_mask:0xf bank_mask:0xf
	v_fmac_f32_dpp v165, v89, v133 row_shr:1 row_mask:0xf bank_mask:0xf
	v_fmac_f32_dpp v166, v90, v134 row_shr:1 row_mask:0xf bank_mask:0xf
	v_fmac_f32_dpp v167, v91, v135 row_shr:1 row_mask:0xf bank_mask:0xf
	v_fmac_f32_dpp v160, v116, v140 row_shl:15 row_mask:0xf bank_mask:0xf
	v_fmac_f32_dpp v161, v117, v141 row_shl:15 row_mask:0xf bank_mask:0xf
	v_fmac_f32_dpp v162, v118, v142 row_shl:15 row_mask:0xf bank_mask:0xf
	v_fmac_f32_dpp v163, v119, v143 row_shl:15 row_mask:0xf bank_mask:0xf
	v_fmac_f32_dpp v164, v104, v132 row_shl:15 row_mask:0xf bank_mask:0xf
	v_fmac_f32_dpp v165, v105, v133 row_shl:15 row_mask:0xf bank_mask:0xf
	v_fmac_f32_dpp v166, v106, v134 row_shl:15 row_mask:0xf bank_mask:0xf
	v_fmac_f32_dpp v167, v107, v135 row_shl:15 row_mask:0xf bank_mask:0xf
	v_fmac_f32_dpp v160, v100, v136 row_shr:2 row_mask:0xf bank_mask:0xf
	v_fmac_f32_dpp v161, v101, v137 row_shr:2 row_mask:0xf bank_mask:0xf
	v_fmac_f32_dpp v162, v102, v138 row_shr:2 row_mask:0xf bank_mask:0xf
	v_fmac_f32_dpp v163, v103, v139 row_shr:2 row_mask:0xf bank_mask:0xf
	v_fmac_f32_dpp v164, v88, v128 row_shr:2 row_mask:0xf bank_mask:0xf
	v_fmac_f32_dpp v165, v89, v129 row_shr:2 row_mask:0xf bank_mask:0xf
	v_fmac_f32_dpp v166, v90, v130 row_shr:2 row_mask:0xf bank_mask:0xf
	v_fmac_f32_dpp v167, v91, v131 row_shr:2 row_mask:0xf bank_mask:0xf
	v_fmac_f32_dpp v160, v116, v136 row_shl:14 row_mask:0xf bank_mask:0xf
	v_fmac_f32_dpp v161, v117, v137 row_shl:14 row_mask:0xf bank_mask:0xf
	v_fmac_f32_dpp v162, v118, v138 row_shl:14 row_mask:0xf bank_mask:0xf
	v_fmac_f32_dpp v163, v119, v139 row_shl:14 row_mask:0xf bank_mask:0xf
	v_fmac_f32_dpp v164, v104, v128 row_shl:14 row_mask:0xf bank_mask:0xf
	v_fmac_f32_dpp v165, v105, v129 row_shl:14 row_mask:0xf bank_mask:0xf
	v_fmac_f32_dpp v166, v106, v130 row_shl:14 row_mask:0xf bank_mask:0xf
	v_fmac_f32_dpp v167, v107, v131 row_shl:14 row_mask:0xf bank_mask:0xf
	v_mul_f32_e32 v168, 0xbfb8aa3b, v160
	v_mul_f32_e32 v169, 0xbfb8aa3b, v161
	v_mul_f32_e32 v170, 0xbfb8aa3b, v162
	v_mul_f32_e32 v171, 0xbfb8aa3b, v163
	v_exp_f32_e32 v168, v168
	v_exp_f32_e32 v169, v169
	v_exp_f32_e32 v170, v170
	v_exp_f32_e32 v171, v171
	v_add_f32_e32 v168, 1.0, v168
	v_add_f32_e32 v169, 1.0, v169
	v_add_f32_e32 v170, 1.0, v170
	v_add_f32_e32 v171, 1.0, v171
	v_rcp_f32_e32 v168, v168
	v_rcp_f32_e32 v169, v169
	v_rcp_f32_e32 v170, v170
	v_rcp_f32_e32 v171, v171
	s_mov_b32 s80, 0x2c000
	s_mov_b32 s81, 0
	v_lshl_add_u64 v[174:175], v[224:225], 0, s[80:81]
	v_mul_f32_e32 v160, v160, v168
	v_mul_f32_e32 v161, v161, v169
	v_mul_f32_e32 v162, v162, v170
	v_mul_f32_e32 v163, v163, v171
	v_mul_f32_e32 v160, v164, v160
	v_mul_f32_e32 v161, v165, v161
	v_mul_f32_e32 v162, v166, v162
	v_mul_f32_e32 v163, v167, v163
	v_cvt_pk_bf16_f32 v172, v160, v161
	v_cvt_pk_bf16_f32 v173, v162, v163
	global_store_dwordx2 v[174:175], v[172:173], off
	v_fma_f32 v208, v152, v84, v156
	v_fma_f32 v209, v153, v85, v157
	v_fma_f32 v210, v154, v86, v158
	v_fma_f32 v211, v155, v87, v159
	v_fma_f32 v212, v144, v72, v148
	v_fma_f32 v213, v145, v73, v149
	v_fma_f32 v214, v146, v74, v150
	v_fma_f32 v215, v147, v75, v151
	v_fmac_f32_dpp v208, v84, v140 row_shr:1 row_mask:0xf bank_mask:0xf
	v_fmac_f32_dpp v209, v85, v141 row_shr:1 row_mask:0xf bank_mask:0xf
	v_fmac_f32_dpp v210, v86, v142 row_shr:1 row_mask:0xf bank_mask:0xf
	v_fmac_f32_dpp v211, v87, v143 row_shr:1 row_mask:0xf bank_mask:0xf
	v_fmac_f32_dpp v212, v72, v132 row_shr:1 row_mask:0xf bank_mask:0xf
	v_fmac_f32_dpp v213, v73, v133 row_shr:1 row_mask:0xf bank_mask:0xf
	v_fmac_f32_dpp v214, v74, v134 row_shr:1 row_mask:0xf bank_mask:0xf
	v_fmac_f32_dpp v215, v75, v135 row_shr:1 row_mask:0xf bank_mask:0xf
	v_fmac_f32_dpp v208, v100, v140 row_shl:15 row_mask:0xf bank_mask:0xf
	v_fmac_f32_dpp v209, v101, v141 row_shl:15 row_mask:0xf bank_mask:0xf
	v_fmac_f32_dpp v210, v102, v142 row_shl:15 row_mask:0xf bank_mask:0xf
	v_fmac_f32_dpp v211, v103, v143 row_shl:15 row_mask:0xf bank_mask:0xf
	v_fmac_f32_dpp v212, v88, v132 row_shl:15 row_mask:0xf bank_mask:0xf
	v_fmac_f32_dpp v213, v89, v133 row_shl:15 row_mask:0xf bank_mask:0xf
	v_fmac_f32_dpp v214, v90, v134 row_shl:15 row_mask:0xf bank_mask:0xf
	v_fmac_f32_dpp v215, v91, v135 row_shl:15 row_mask:0xf bank_mask:0xf
	v_fmac_f32_dpp v208, v84, v136 row_shr:2 row_mask:0xf bank_mask:0xf
	v_fmac_f32_dpp v209, v85, v137 row_shr:2 row_mask:0xf bank_mask:0xf
; DI float silu_fast(float x) { return x * __builtin_amdgcn_rcpf(1.f + __expf(-x)); }
; template <int CTRL> DI float dppf(float v) { return __builtin_bit_cast(float, __builtin_amdgcn_update_dpp(0, __builtin_bit_cast(int, v), CTRL, 0xf, 0xf, true)); }
; DI void Epi::fused(const f32x4 (&acc)[2][2][4][2], int pm, int pn, int wr, int wc, int fr, int fq) const {
;     ...
;     for (int bj = 0; bj < 2; ++bj) {
;         const int ncol = pn * 256 + bj * 128 + wc * 32 + 8 * fq, j0 = (ncol >> 3) * 4;
;         const f32x4 wa0 = *(const f32x4*)(E.cf0 + j0), wa1 = *(const f32x4*)(E.cf0 + FF2 + j0), wa2 = *(const f32x4*)(E.cf0 + 2 * FF2 + j0);
;         const f32x4 wb0 = *(const f32x4*)(E.cf0 + FFH + j0), wb1 = *(const f32x4*)(E.cf0 + FF2 + FFH + j0), wb2 = *(const f32x4*)(E.cf0 + 2 * FF2 + FFH + j0);
;         const f32x4 ba = *(const f32x4*)(E.cf1 + j0), bb = *(const f32x4*)(E.cf1 + FFH + j0);
; #pragma unroll
;         for (int ai = 0; ai < 2; ++ai) {
;             f32x4 pa = (f32x4){0.f, 0.f, 0.f, 0.f}, pb = pa;
; #pragma unroll
;             for (int m = 0; m < 4; ++m) {
;                 const f32x4 ca = acc[ai][bj][m][0], cb = acc[ai][bj][m][1];
;                 const int row = pm * 256 + ai * 128 + wr * 64 + m * 16 + fr;
;                 float o[4];
; #pragma unroll
;                 for (int e = 0; e < 4; ++e) {
;                     const float a1 = dppf<0x111>(ca[e]) + dppf<0x10F>(pa[e]), a2 = dppf<0x112>(ca[e]) + dppf<0x10E>(pa[e]);
;                     const float b1 = dppf<0x111>(cb[e]) + dppf<0x10F>(pb[e]), b2 = dppf<0x112>(cb[e]) + dppf<0x10E>(pb[e]);
;                     const float ya = fmaf(wa0[e], a2, fmaf(wa1[e], a1, fmaf(wa2[e], ca[e], ba[e])));
;                     const float yb = fmaf(wb0[e], b2, fmaf(wb1[e], b1, fmaf(wb2[e], cb[e], bb[e])));
;                     o[e] = silu_fast(ya) * yb; }
;                 if (m > 0 || fr >= 2) { u32x2 w; w.x = pk2(o[0], o[1]); w.y = pk2(o[2], o[3]); *(u32x2*)(E.d0 + (size_t)row * FFH + j0) = w; }
;                 if ((m == 0 && fr < 2) || (m == 3 && fr >= 14)) { float* hb = E.f0 + ((size_t)(row >> 6) * 4 + (m == 0 ? fr : fr - 12)) * FF2 + ncol; *(f32x4*)hb = ca; *(f32x4*)(hb + 4) = cb; }
;                 pa = ca; pb = cb;
	v_fmac_f32_dpp v210, v86, v138 row_shr:2 row_mask:0xf bank_mask:0xf
	v_fmac_f32_dpp v211, v87, v139 row_shr:2 row_mask:0xf bank_mask:0xf
	v_fmac_f32_dpp v212, v72, v128 row_shr:2 row_mask:0xf bank_mask:0xf
	v_fmac_f32_dpp v213, v73, v129 row_shr:2 row_mask:0xf bank_mask:0xf
	v_fmac_f32_dpp v214, v74, v130 row_shr:2 row_mask:0xf bank_mask:0xf
	v_fmac_f32_dpp v215, v75, v131 row_shr:2 row_mask:0xf bank_mask:0xf
	v_fmac_f32_dpp v208, v100, v136 row_shl:14 row_mask:0xf bank_mask:0xf
	v_fmac_f32_dpp v209, v101, v137 row_shl:14 row_mask:0xf bank_mask:0xf
	v_fmac_f32_dpp v210, v102, v138 row_shl:14 row_mask:0xf bank_mask:0xf
	v_fmac_f32_dpp v211, v103, v139 row_shl:14 row_mask:0xf bank_mask:0xf
	v_fmac_f32_dpp v212, v88, v128 row_shl:14 row_mask:0xf bank_mask:0xf
	v_fmac_f32_dpp v213, v89, v129 row_shl:14 row_mask:0xf bank_mask:0xf
	v_fmac_f32_dpp v214, v90, v130 row_shl:14 row_mask:0xf bank_mask:0xf
	v_fmac_f32_dpp v215, v91, v131 row_shl:14 row_mask:0xf bank_mask:0xf
	v_mul_f32_e32 v216, 0xbfb8aa3b, v208
	v_mul_f32_e32 v217, 0xbfb8aa3b, v209
	v_mul_f32_e32 v218, 0xbfb8aa3b, v210
	v_mul_f32_e32 v219, 0xbfb8aa3b, v211
	v_exp_f32_e32 v216, v216
	v_exp_f32_e32 v217, v217
	v_exp_f32_e32 v218, v218
	v_exp_f32_e32 v219, v219
	v_add_f32_e32 v216, 1.0, v216
	v_add_f32_e32 v217, 1.0, v217
	v_add_f32_e32 v218, 1.0, v218
	v_add_f32_e32 v219, 1.0, v219
	v_rcp_f32_e32 v216, v216
	v_rcp_f32_e32 v217, v217
	v_rcp_f32_e32 v218, v218
	v_rcp_f32_e32 v219, v219
	s_mov_b32 s80, 0x42000
	s_mov_b32 s81, 0
	v_lshl_add_u64 v[222:223], v[224:225], 0, s[80:81]
	v_mul_f32_e32 v208, v208, v216
	v_mul_f32_e32 v209, v209, v217
	v_mul_f32_e32 v210, v210, v218
	v_mul_f32_e32 v211, v211, v219
	v_mul_f32_e32 v208, v212, v208
	v_mul_f32_e32 v209, v213, v209
	v_mul_f32_e32 v210, v214, v210
	v_mul_f32_e32 v211, v215, v211
	v_cvt_pk_bf16_f32 v220, v208, v209
	v_cvt_pk_bf16_f32 v221, v210, v211
	global_store_dwordx2 v[222:223], v[220:221], off
	s_ashr_i32 s80, s71, 6
	s_lshl_b32 s80, s80, 2
	v_add_u32_e32 v226, s80, v190
	v_mov_b64_e32 v[222:223], s[8:9]
	s_movk_i32 s80, 0x5800
	v_mad_i64_i32 v[222:223], s[78:79], v226, s80, v[222:223]
	v_lshl_add_u64 v[222:223], v[228:229], 2, v[222:223]
	s_and_saveexec_b64 s[76:77], s[42:43]
	global_store_dwordx4 v[222:223], v[84:87], off
	global_store_dwordx4 v[222:223], v[72:75], off offset:16
	s_or_b64 exec, exec, s[76:77]
	v_add_u32_e32 v238, 0x80, v240
	v_lshlrev_b32_e32 v238, 1, v238
	v_mov_b32_e32 v239, 0
	v_lshl_add_u64 v[84:85], s[22:23], 0, v[238:239]
	global_load_dwordx4 v[84:87], v[84:85], off
	v_readlane_b32 s76, v254, 54
	v_readlane_b32 s77, v254, 55
	s_nop 1
	v_lshl_add_u64 v[88:89], s[76:77], 0, v[238:239]
	global_load_dwordx4 v[88:91], v[88:89], off
	v_readlane_b32 s76, v254, 56
	v_readlane_b32 s77, v254, 57
	s_nop 1
	v_lshl_add_u64 v[100:101], s[76:77], 0, v[238:239]
	global_load_dwordx4 v[100:103], v[100:101], off
	v_readlane_b32 s76, v255, 4
	v_readlane_b32 s77, v255, 5
	s_nop 1
	v_lshl_add_u64 v[104:105], s[76:77], 0, v[238:239]
	global_load_dwordx4 v[104:107], v[104:105], off
	v_readlane_b32 s76, v255, 6
	v_readlane_b32 s77, v255, 7
	s_nop 1
	v_lshl_add_u64 v[116:117], s[76:77], 0, v[238:239]
	global_load_dwordx4 v[116:119], v[116:117], off
	v_readlane_b32 s76, v255, 8
	v_readlane_b32 s77, v255, 9
	s_nop 1
	v_lshl_add_u64 v[120:121], s[76:77], 0, v[238:239]
	global_load_dwordx4 v[120:123], v[120:121], off
	v_readlane_b32 s76, v254, 49
	v_readlane_b32 s77, v254, 50
	s_nop 1
	v_lshl_add_u64 v[124:125], s[76:77], 0, v[238:239]
	global_load_dwordx4 v[124:127], v[124:125], off
	v_lshl_add_u64 v[72:73], s[72:73], 0, v[238:239]
	global_load_dwordx4 v[72:75], v[72:73], off
	v_add_u32_e32 v228, 128, v199
	v_mov_b64_e32 v[224:225], s[12:13]
	s_movk_i32 s80, 0x1600
	v_mad_i64_i32 v[224:225], s[78:79], v228, s80, v[224:225]
	v_mov_b32_e32 v228, v240
	v_mov_b32_e32 v229, 0
	v_lshl_add_u64 v[224:225], v[228:229], 0, v[224:225]
	v_fma_f32 v160, v152, v60, v156
	v_fma_f32 v161, v153, v61, v157
	v_fma_f32 v162, v154, v62, v158
	v_fma_f32 v163, v155, v63, v159
	v_fma_f32 v164, v144, v56, v148
	v_fma_f32 v165, v145, v57, v149
	v_fma_f32 v166, v146, v58, v150
	v_fma_f32 v167, v147, v59, v151
	v_fmac_f32_dpp v160, v60, v140 row_shr:1 row_mask:0xf bank_mask:0xf
	v_fmac_f32_dpp v161, v61, v141 row_shr:1 row_mask:0xf bank_mask:0xf
	v_fmac_f32_dpp v162, v62, v142 row_shr:1 row_mask:0xf bank_mask:0xf
	v_fmac_f32_dpp v163, v63, v143 row_shr:1 row_mask:0xf bank_mask:0xf
	v_fmac_f32_dpp v164, v56, v132 row_shr:1 row_mask:0xf bank_mask:0xf
	v_fmac_f32_dpp v165, v57, v133 row_shr:1 row_mask:0xf bank_mask:0xf
	v_fmac_f32_dpp v166, v58, v134 row_shr:1 row_mask:0xf bank_mask:0xf
	v_fmac_f32_dpp v167, v59, v135 row_shr:1 row_mask:0xf bank_mask:0xf
	v_fmac_f32_dpp v160, v60, v136 row_shr:2 row_mask:0xf bank_mask:0xf
	v_fmac_f32_dpp v161, v61, v137 row_shr:2 row_mask:0xf bank_mask:0xf
	v_fmac_f32_dpp v162, v62, v138 row_shr:2 row_mask:0xf bank_mask:0xf
	v_fmac_f32_dpp v163, v63, v139 row_shr:2 row_mask:0xf bank_mask:0xf
	v_fmac_f32_dpp v164, v56, v128 row_shr:2 row_mask:0xf bank_mask:0xf
	v_fmac_f32_dpp v165, v57, v129 row_shr:2 row_mask:0xf bank_mask:0xf
	v_fmac_f32_dpp v166, v58, v130 row_shr:2 row_mask:0xf bank_mask:0xf
	v_fmac_f32_dpp v167, v59, v131 row_shr:2 row_mask:0xf bank_mask:0xf
	v_mul_f32_e32 v168, 0xbfb8aa3b, v160
	v_mul_f32_e32 v169, 0xbfb8aa3b, v161
	v_mul_f32_e32 v170, 0xbfb8aa3b, v162
	v_mul_f32_e32 v171, 0xbfb8aa3b, v163
	v_exp_f32_e32 v168, v168
	v_exp_f32_e32 v169, v169
	v_exp_f32_e32 v170, v170
	v_exp_f32_e32 v171, v171
	v_add_f32_e32 v168, 1.0, v168
	v_add_f32_e32 v169, 1.0, v169
	v_add_f32_e32 v170, 1.0, v170
	v_add_f32_e32 v171, 1.0, v171
; DI float silu_fast(float x) { return x * __builtin_amdgcn_rcpf(1.f + __expf(-x)); }
; template <int CTRL> DI float dppf(float v) { return __builtin_bit_cast(float, __builtin_amdgcn_update_dpp(0, __builtin_bit_cast(int, v), CTRL, 0xf, 0xf, true)); }
; DI void Epi::fused(const f32x4 (&acc)[2][2][4][2], int pm, int pn, int wr, int wc, int fr, int fq) const {
;     ...
;     for (int bj = 0; bj < 2; ++bj) {
;         const int ncol = pn * 256 + bj * 128 + wc * 32 + 8 * fq, j0 = (ncol >> 3) * 4;
;         const f32x4 wa0 = *(const f32x4*)(E.cf0 + j0), wa1 = *(const f32x4*)(E.cf0 + FF2 + j0), wa2 = *(const f32x4*)(E.cf0 + 2 * FF2 + j0);
;         const f32x4 wb0 = *(const f32x4*)(E.cf0 + FFH + j0), wb1 = *(const f32x4*)(E.cf0 + FF2 + FFH + j0), wb2 = *(const f32x4*)(E.cf0 + 2 * FF2 + FFH + j0);
;         const f32x4 ba = *(const f32x4*)(E.cf1 + j0), bb = *(const f32x4*)(E.cf1 + FFH + j0);
; #pragma unroll
;         for (int ai = 0; ai < 2; ++ai) {
;             f32x4 pa = (f32x4){0.f, 0.f, 0.f, 0.f}, pb = pa;
; #pragma unroll
;             for (int m = 0; m < 4; ++m) {
;                 const f32x4 ca = acc[ai][bj][m][0], cb = acc[ai][bj][m][1];
;                 const int row = pm * 256 + ai * 128 + wr * 64 + m * 16 + fr;
;                 float o[4];
; #pragma unroll
;                 for (int e = 0; e < 4; ++e) {
;                     const float a1 = dppf<0x111>(ca[e]) + dppf<0x10F>(pa[e]), a2 = dppf<0x112>(ca[e]) + dppf<0x10E>(pa[e]);
;                     const float b1 = dppf<0x111>(cb[e]) + dppf<0x10F>(pb[e]), b2 = dppf<0x112>(cb[e]) + dppf<0x10E>(pb[e]);
;                     const float ya = fmaf(wa0[e], a2, fmaf(wa1[e], a1, fmaf(wa2[e], ca[e], ba[e])));
;                     const float yb = fmaf(wb0[e], b2, fmaf(wb1[e], b1, fmaf(wb2[e], cb[e], bb[e])));
;                     o[e] = silu_fast(ya) * yb; }
;                 if (m > 0 || fr >= 2) { u32x2 w; w.x = pk2(o[0], o[1]); w.y = pk2(o[2], o[3]); *(u32x2*)(E.d0 + (size_t)row * FFH + j0) = w; }
;                 if ((m == 0 && fr < 2) || (m == 3 && fr >= 14)) { float* hb = E.f0 + ((size_t)(row >> 6) * 4 + (m == 0 ? fr : fr - 12)) * FF2 + ncol; *(f32x4*)hb = ca; *(f32x4*)(hb + 4) = cb; }
;                 pa = ca; pb = cb;
	v_rcp_f32_e32 v168, v168
	v_rcp_f32_e32 v169, v169
	v_rcp_f32_e32 v170, v170
	v_rcp_f32_e32 v171, v171
	v_mov_b64_e32 v[174:175], v[224:225]
	v_mul_f32_e32 v160, v160, v168
	v_mul_f32_e32 v161, v161, v169
	v_mul_f32_e32 v162, v162, v170
	v_mul_f32_e32 v163, v163, v171
	v_mul_f32_e32 v160, v164, v160
	v_mul_f32_e32 v161, v165, v161
	v_mul_f32_e32 v162, v166, v162
	v_mul_f32_e32 v163, v167, v163
	v_cvt_pk_bf16_f32 v172, v160, v161
	v_cvt_pk_bf16_f32 v173, v162, v163
	s_and_saveexec_b64 s[76:77], s[38:39]
	global_store_dwordx2 v[174:175], v[172:173], off
	s_or_b64 exec, exec, s[76:77]
	s_ashr_i32 s80, s71, 6
	s_lshl_b32 s80, s80, 2
	s_add_i32 s80, s80, 8
	v_add_u32_e32 v226, s80, v188
	v_mov_b64_e32 v[174:175], s[8:9]
	s_movk_i32 s80, 0x5800
	v_mad_i64_i32 v[174:175], s[78:79], v226, s80, v[174:175]
	v_lshl_add_u64 v[174:175], v[228:229], 2, v[174:175]
	s_and_saveexec_b64 s[76:77], s[40:41]
	global_store_dwordx4 v[174:175], v[60:63], off
	global_store_dwordx4 v[174:175], v[56:59], off offset:16
	s_or_b64 exec, exec, s[76:77]
	v_fma_f32 v208, v152, v52, v156
	v_fma_f32 v209, v153, v53, v157
	v_fma_f32 v210, v154, v54, v158
	v_fma_f32 v211, v155, v55, v159
	v_fma_f32 v212, v144, v40, v148
	v_fma_f32 v213, v145, v41, v149
	v_fma_f32 v214, v146, v42, v150
	v_fma_f32 v215, v147, v43, v151
	v_fmac_f32_dpp v208, v52, v140 row_shr:1 row_mask:0xf bank_mask:0xf
	v_fmac_f32_dpp v209, v53, v141 row_shr:1 row_mask:0xf bank_mask:0xf
	v_fmac_f32_dpp v210, v54, v142 row_shr:1 row_mask:0xf bank_mask:0xf
	v_fmac_f32_dpp v211, v55, v143 row_shr:1 row_mask:0xf bank_mask:0xf
	v_fmac_f32_dpp v212, v40, v132 row_shr:1 row_mask:0xf bank_mask:0xf
	v_fmac_f32_dpp v213, v41, v133 row_shr:1 row_mask:0xf bank_mask:0xf
	v_fmac_f32_dpp v214, v42, v134 row_shr:1 row_mask:0xf bank_mask:0xf
	v_fmac_f32_dpp v215, v43, v135 row_shr:1 row_mask:0xf bank_mask:0xf
	v_fmac_f32_dpp v208, v60, v140 row_shl:15 row_mask:0xf bank_mask:0xf
	v_fmac_f32_dpp v209, v61, v141 row_shl:15 row_mask:0xf bank_mask:0xf
	v_fmac_f32_dpp v210, v62, v142 row_shl:15 row_mask:0xf bank_mask:0xf
	v_fmac_f32_dpp v211, v63, v143 row_shl:15 row_mask:0xf bank_mask:0xf
	v_fmac_f32_dpp v212, v56, v132 row_shl:15 row_mask:0xf bank_mask:0xf
	v_fmac_f32_dpp v213, v57, v133 row_shl:15 row_mask:0xf bank_mask:0xf
	v_fmac_f32_dpp v214, v58, v134 row_shl:15 row_mask:0xf bank_mask:0xf
	v_fmac_f32_dpp v215, v59, v135 row_shl:15 row_mask:0xf bank_mask:0xf
	v_fmac_f32_dpp v208, v52, v136 row_shr:2 row_mask:0xf bank_mask:0xf
	v_fmac_f32_dpp v209, v53, v137 row_shr:2 row_mask:0xf bank_mask:0xf
	v_fmac_f32_dpp v210, v54, v138 row_shr:2 row_mask:0xf bank_mask:0xf
	v_fmac_f32_dpp v211, v55, v139 row_shr:2 row_mask:0xf bank_mask:0xf
	v_fmac_f32_dpp v212, v40, v128 row_shr:2 row_mask:0xf bank_mask:0xf
	v_fmac_f32_dpp v213, v41, v129 row_shr:2 row_mask:0xf bank_mask:0xf
	v_fmac_f32_dpp v214, v42, v130 row_shr:2 row_mask:0xf bank_mask:0xf
	v_fmac_f32_dpp v215, v43, v131 row_shr:2 row_mask:0xf bank_mask:0xf
	v_fmac_f32_dpp v208, v60, v136 row_shl:14 row_mask:0xf bank_mask:0xf
	v_fmac_f32_dpp v209, v61, v137 row_shl:14 row_mask:0xf bank_mask:0xf
	v_fmac_f32_dpp v210, v62, v138 row_shl:14 row_mask:0xf bank_mask:0xf
	v_fmac_f32_dpp v211, v63, v139 row_shl:14 row_mask:0xf bank_mask:0xf
	v_fmac_f32_dpp v212, v56, v128 row_shl:14 row_mask:0xf bank_mask:0xf
	v_fmac_f32_dpp v213, v57, v129 row_shl:14 row_mask:0xf bank_mask:0xf
	v_fmac_f32_dpp v214, v58, v130 row_shl:14 row_mask:0xf bank_mask:0xf
	v_fmac_f32_dpp v215, v59, v131 row_shl:14 row_mask:0xf bank_mask:0xf
	v_mul_f32_e32 v216, 0xbfb8aa3b, v208
	v_mul_f32_e32 v217, 0xbfb8aa3b, v209
	v_mul_f32_e32 v218, 0xbfb8aa3b, v210
	v_mul_f32_e32 v219, 0xbfb8aa3b, v211
	v_exp_f32_e32 v216, v216
	v_exp_f32_e32 v217, v217
	v_exp_f32_e32 v218, v218
	v_exp_f32_e32 v219, v219
	v_add_f32_e32 v216, 1.0, v216
	v_add_f32_e32 v217, 1.0, v217
	v_add_f32_e32 v218, 1.0, v218
	v_add_f32_e32 v219, 1.0, v219
	v_rcp_f32_e32 v216, v216
	v_rcp_f32_e32 v217, v217
	v_rcp_f32_e32 v218, v218
	v_rcp_f32_e32 v219, v219
	s_mov_b32 s80, 0x16000
	s_mov_b32 s81, 0
	v_lshl_add_u64 v[222:223], v[224:225], 0, s[80:81]
	v_mul_f32_e32 v208, v208, v216
	v_mul_f32_e32 v209, v209, v217
	v_mul_f32_e32 v210, v210, v218
	v_mul_f32_e32 v211, v211, v219
	v_mul_f32_e32 v208, v212, v208
	v_mul_f32_e32 v209, v213, v209
	v_mul_f32_e32 v210, v214, v210
	v_mul_f32_e32 v211, v215, v211
	v_cvt_pk_bf16_f32 v220, v208, v209
	v_cvt_pk_bf16_f32 v221, v210, v211
	global_store_dwordx2 v[222:223], v[220:221], off
	v_fma_f32 v160, v152, v36, v156
	v_fma_f32 v161, v153, v37, v157
	v_fma_f32 v162, v154, v38, v158
	v_fma_f32 v163, v155, v39, v159
	v_fma_f32 v164, v144, v16, v148
	v_fma_f32 v165, v145, v17, v149
	v_fma_f32 v166, v146, v18, v150
	v_fma_f32 v167, v147, v19, v151
	v_fmac_f32_dpp v160, v36, v140 row_shr:1 row_mask:0xf bank_mask:0xf
	v_fmac_f32_dpp v161, v37, v141 row_shr:1 row_mask:0xf bank_mask:0xf
	v_fmac_f32_dpp v162, v38, v142 row_shr:1 row_mask:0xf bank_mask:0xf
	v_fmac_f32_dpp v163, v39, v143 row_shr:1 row_mask:0xf bank_mask:0xf
	v_fmac_f32_dpp v164, v16, v132 row_shr:1 row_mask:0xf bank_mask:0xf
	v_fmac_f32_dpp v165, v17, v133 row_shr:1 row_mask:0xf bank_mask:0xf
	v_fmac_f32_dpp v166, v18, v134 row_shr:1 row_mask:0xf bank_mask:0xf
	v_fmac_f32_dpp v167, v19, v135 row_shr:1 row_mask:0xf bank_mask:0xf
	v_fmac_f32_dpp v160, v52, v140 row_shl:15 row_mask:0xf bank_mask:0xf
	v_fmac_f32_dpp v161, v53, v141 row_shl:15 row_mask:0xf bank_mask:0xf
	v_fmac_f32_dpp v162, v54, v142 row_shl:15 row_mask:0xf bank_mask:0xf
	v_fmac_f32_dpp v163, v55, v143 row_shl:15 row_mask:0xf bank_mask:0xf
	v_fmac_f32_dpp v164, v40, v132 row_shl:15 row_mask:0xf bank_mask:0xf
; DI float silu_fast(float x) { return x * __builtin_amdgcn_rcpf(1.f + __expf(-x)); }
; template <int CTRL> DI float dppf(float v) { return __builtin_bit_cast(float, __builtin_amdgcn_update_dpp(0, __builtin_bit_cast(int, v), CTRL, 0xf, 0xf, true)); }
; DI void Epi::fused(const f32x4 (&acc)[2][2][4][2], int pm, int pn, int wr, int wc, int fr, int fq) const {
;     ...
;     for (int bj = 0; bj < 2; ++bj) {
;         const int ncol = pn * 256 + bj * 128 + wc * 32 + 8 * fq, j0 = (ncol >> 3) * 4;
;         const f32x4 wa0 = *(const f32x4*)(E.cf0 + j0), wa1 = *(const f32x4*)(E.cf0 + FF2 + j0), wa2 = *(const f32x4*)(E.cf0 + 2 * FF2 + j0);
;         const f32x4 wb0 = *(const f32x4*)(E.cf0 + FFH + j0), wb1 = *(const f32x4*)(E.cf0 + FF2 + FFH + j0), wb2 = *(const f32x4*)(E.cf0 + 2 * FF2 + FFH + j0);
;         const f32x4 ba = *(const f32x4*)(E.cf1 + j0), bb = *(const f32x4*)(E.cf1 + FFH + j0);
; #pragma unroll
;         for (int ai = 0; ai < 2; ++ai) {
;             f32x4 pa = (f32x4){0.f, 0.f, 0.f, 0.f}, pb = pa;
; #pragma unroll
;             for (int m = 0; m < 4; ++m) {
;                 const f32x4 ca = acc[ai][bj][m][0], cb = acc[ai][bj][m][1];
;                 const int row = pm * 256 + ai * 128 + wr * 64 + m * 16 + fr;
;                 float o[4];
; #pragma unroll
;                 for (int e = 0; e < 4; ++e) {
;                     const float a1 = dppf<0x111>(ca[e]) + dppf<0x10F>(pa[e]), a2 = dppf<0x112>(ca[e]) + dppf<0x10E>(pa[e]);
;                     const float b1 = dppf<0x111>(cb[e]) + dppf<0x10F>(pb[e]), b2 = dppf<0x112>(cb[e]) + dppf<0x10E>(pb[e]);
;                     const float ya = fmaf(wa0[e], a2, fmaf(wa1[e], a1, fmaf(wa2[e], ca[e], ba[e])));
;                     const float yb = fmaf(wb0[e], b2, fmaf(wb1[e], b1, fmaf(wb2[e], cb[e], bb[e])));
;                     o[e] = silu_fast(ya) * yb; }
;                 if (m > 0 || fr >= 2) { u32x2 w; w.x = pk2(o[0], o[1]); w.y = pk2(o[2], o[3]); *(u32x2*)(E.d0 + (size_t)row * FFH + j0) = w; }
;                 if ((m == 0 && fr < 2) || (m == 3 && fr >= 14)) { float* hb = E.f0 + ((size_t)(row >> 6) * 4 + (m == 0 ? fr : fr - 12)) * FF2 + ncol; *(f32x4*)hb = ca; *(f32x4*)(hb + 4) = cb; }
;                 pa = ca; pb = cb;
	v_fmac_f32_dpp v165, v41, v133 row_shl:15 row_mask:0xf bank_mask:0xf
	v_fmac_f32_dpp v166, v42, v134 row_shl:15 row_mask:0xf bank_mask:0xf
	v_fmac_f32_dpp v167, v43, v135 row_shl:15 row_mask:0xf bank_mask:0xf
	v_fmac_f32_dpp v160, v36, v136 row_shr:2 row_mask:0xf bank_mask:0xf
	v_fmac_f32_dpp v161, v37, v137 row_shr:2 row_mask:0xf bank_mask:0xf
	v_fmac_f32_dpp v162, v38, v138 row_shr:2 row_mask:0xf bank_mask:0xf
	v_fmac_f32_dpp v163, v39, v139 row_shr:2 row_mask:0xf bank_mask:0xf
	v_fmac_f32_dpp v164, v16, v128 row_shr:2 row_mask:0xf bank_mask:0xf
	v_fmac_f32_dpp v165, v17, v129 row_shr:2 row_mask:0xf bank_mask:0xf
	v_fmac_f32_dpp v166, v18, v130 row_shr:2 row_mask:0xf bank_mask:0xf
	v_fmac_f32_dpp v167, v19, v131 row_shr:2 row_mask:0xf bank_mask:0xf
	v_fmac_f32_dpp v160, v52, v136 row_shl:14 row_mask:0xf bank_mask:0xf
	v_fmac_f32_dpp v161, v53, v137 row_shl:14 row_mask:0xf bank_mask:0xf
	v_fmac_f32_dpp v162, v54, v138 row_shl:14 row_mask:0xf bank_mask:0xf
	v_fmac_f32_dpp v163, v55, v139 row_shl:14 row_mask:0xf bank_mask:0xf
	v_fmac_f32_dpp v164, v40, v128 row_shl:14 row_mask:0xf bank_mask:0xf
	v_fmac_f32_dpp v165, v41, v129 row_shl:14 row_mask:0xf bank_mask:0xf
	v_fmac_f32_dpp v166, v42, v130 row_shl:14 row_mask:0xf bank_mask:0xf
	v_fmac_f32_dpp v167, v43, v131 row_shl:14 row_mask:0xf bank_mask:0xf
	v_mul_f32_e32 v168, 0xbfb8aa3b, v160
	v_mul_f32_e32 v169, 0xbfb8aa3b, v161
	v_mul_f32_e32 v170, 0xbfb8aa3b, v162
	v_mul_f32_e32 v171, 0xbfb8aa3b, v163
	v_exp_f32_e32 v168, v168
	v_exp_f32_e32 v169, v169
	v_exp_f32_e32 v170, v170
	v_exp_f32_e32 v171, v171
	v_add_f32_e32 v168, 1.0, v168
	v_add_f32_e32 v169, 1.0, v169
	v_add_f32_e32 v170, 1.0, v170
	v_add_f32_e32 v171, 1.0, v171
	v_rcp_f32_e32 v168, v168
	v_rcp_f32_e32 v169, v169
	v_rcp_f32_e32 v170, v170
	v_rcp_f32_e32 v171, v171
	s_mov_b32 s80, 0x2c000
	s_mov_b32 s81, 0
	v_lshl_add_u64 v[174:175], v[224:225], 0, s[80:81]
	v_mul_f32_e32 v160, v160, v168
	v_mul_f32_e32 v161, v161, v169
	v_mul_f32_e32 v162, v162, v170
	v_mul_f32_e32 v163, v163, v171
	v_mul_f32_e32 v160, v164, v160
	v_mul_f32_e32 v161, v165, v161
	v_mul_f32_e32 v162, v166, v162
	v_mul_f32_e32 v163, v167, v163
	v_cvt_pk_bf16_f32 v172, v160, v161
	v_cvt_pk_bf16_f32 v173, v162, v163
	global_store_dwordx2 v[174:175], v[172:173], off
	v_fma_f32 v208, v152, v12, v156
	v_fma_f32 v209, v153, v13, v157
	v_fma_f32 v210, v154, v14, v158
	v_fma_f32 v211, v155, v15, v159
	v_fma_f32 v212, v144, v0, v148
	v_fma_f32 v213, v145, v1, v149
	v_fma_f32 v214, v146, v2, v150
	v_fma_f32 v215, v147, v3, v151
	v_fmac_f32_dpp v208, v12, v140 row_shr:1 row_mask:0xf bank_mask:0xf
	v_fmac_f32_dpp v209, v13, v141 row_shr:1 row_mask:0xf bank_mask:0xf
	v_fmac_f32_dpp v210, v14, v142 row_shr:1 row_mask:0xf bank_mask:0xf
	v_fmac_f32_dpp v211, v15, v143 row_shr:1 row_mask:0xf bank_mask:0xf
	v_fmac_f32_dpp v212, v0, v132 row_shr:1 row_mask:0xf bank_mask:0xf
	v_fmac_f32_dpp v213, v1, v133 row_shr:1 row_mask:0xf bank_mask:0xf
	v_fmac_f32_dpp v214, v2, v134 row_shr:1 row_mask:0xf bank_mask:0xf
	v_fmac_f32_dpp v215, v3, v135 row_shr:1 row_mask:0xf bank_mask:0xf
	v_fmac_f32_dpp v208, v36, v140 row_shl:15 row_mask:0xf bank_mask:0xf
	v_fmac_f32_dpp v209, v37, v141 row_shl:15 row_mask:0xf bank_mask:0xf
	v_fmac_f32_dpp v210, v38, v142 row_shl:15 row_mask:0xf bank_mask:0xf
	v_fmac_f32_dpp v211, v39, v143 row_shl:15 row_mask:0xf bank_mask:0xf
	v_fmac_f32_dpp v212, v16, v132 row_shl:15 row_mask:0xf bank_mask:0xf
	v_fmac_f32_dpp v213, v17, v133 row_shl:15 row_mask:0xf bank_mask:0xf
	v_fmac_f32_dpp v214, v18, v134 row_shl:15 row_mask:0xf bank_mask:0xf
	v_fmac_f32_dpp v215, v19, v135 row_shl:15 row_mask:0xf bank_mask:0xf
	v_fmac_f32_dpp v208, v12, v136 row_shr:2 row_mask:0xf bank_mask:0xf
	v_fmac_f32_dpp v209, v13, v137 row_shr:2 row_mask:0xf bank_mask:0xf
	v_fmac_f32_dpp v210, v14, v138 row_shr:2 row_mask:0xf bank_mask:0xf
	v_fmac_f32_dpp v211, v15, v139 row_shr:2 row_mask:0xf bank_mask:0xf
	v_fmac_f32_dpp v212, v0, v128 row_shr:2 row_mask:0xf bank_mask:0xf
	v_fmac_f32_dpp v213, v1, v129 row_shr:2 row_mask:0xf bank_mask:0xf
	v_fmac_f32_dpp v214, v2, v130 row_shr:2 row_mask:0xf bank_mask:0xf
	v_fmac_f32_dpp v215, v3, v131 row_shr:2 row_mask:0xf bank_mask:0xf
	v_fmac_f32_dpp v208, v36, v136 row_shl:14 row_mask:0xf bank_mask:0xf
	v_fmac_f32_dpp v209, v37, v137 row_shl:14 row_mask:0xf bank_mask:0xf
	v_fmac_f32_dpp v210, v38, v138 row_shl:14 row_mask:0xf bank_mask:0xf
	v_fmac_f32_dpp v211, v39, v139 row_shl:14 row_mask:0xf bank_mask:0xf
	v_fmac_f32_dpp v212, v16, v128 row_shl:14 row_mask:0xf bank_mask:0xf
	v_fmac_f32_dpp v213, v17, v129 row_shl:14 row_mask:0xf bank_mask:0xf
	v_fmac_f32_dpp v214, v18, v130 row_shl:14 row_mask:0xf bank_mask:0xf
	v_fmac_f32_dpp v215, v19, v131 row_shl:14 row_mask:0xf bank_mask:0xf
	v_mul_f32_e32 v216, 0xbfb8aa3b, v208
	v_mul_f32_e32 v217, 0xbfb8aa3b, v209
	v_mul_f32_e32 v218, 0xbfb8aa3b, v210
	v_mul_f32_e32 v219, 0xbfb8aa3b, v211
	v_exp_f32_e32 v216, v216
	v_exp_f32_e32 v217, v217
	v_exp_f32_e32 v218, v218
	v_exp_f32_e32 v219, v219
	v_add_f32_e32 v216, 1.0, v216
	v_add_f32_e32 v217, 1.0, v217
	v_add_f32_e32 v218, 1.0, v218
	v_add_f32_e32 v219, 1.0, v219
	v_rcp_f32_e32 v216, v216
	v_rcp_f32_e32 v217, v217
	v_rcp_f32_e32 v218, v218
	v_rcp_f32_e32 v219, v219
	s_mov_b32 s80, 0x42000
	s_mov_b32 s81, 0
	v_lshl_add_u64 v[222:223], v[224:225], 0, s[80:81]
	v_mul_f32_e32 v208, v208, v216
	v_mul_f32_e32 v209, v209, v217
	v_mul_f32_e32 v210, v210, v218
	v_mul_f32_e32 v211, v211, v219
	v_mul_f32_e32 v208, v212, v208
	v_mul_f32_e32 v209, v213, v209
	v_mul_f32_e32 v210, v214, v210
	v_mul_f32_e32 v211, v215, v211
	v_cvt_pk_bf16_f32 v220, v208, v209
	v_cvt_pk_bf16_f32 v221, v210, v211
	global_store_dwordx2 v[222:223], v[220:221], off
	s_ashr_i32 s80, s71, 6
	s_lshl_b32 s80, s80, 2
	s_add_i32 s80, s80, 8
	v_add_u32_e32 v226, s80, v190
	v_mov_b64_e32 v[222:223], s[8:9]
	s_movk_i32 s80, 0x5800
	v_mad_i64_i32 v[222:223], s[78:79], v226, s80, v[222:223]
	v_lshl_add_u64 v[222:223], v[228:229], 2, v[222:223]
	s_and_saveexec_b64 s[76:77], s[42:43]
	global_store_dwordx4 v[222:223], v[12:15], off
	global_store_dwordx4 v[222:223], v[0:3], off offset:16
	s_or_b64 exec, exec, s[76:77]
	v_mov_b32_e32 v228, v199
	v_mov_b64_e32 v[224:225], s[12:13]
	s_movk_i32 s80, 0x1600
	v_mad_i64_i32 v[224:225], s[78:79], v228, s80, v[224:225]
	v_add_u32_e32 v228, 128, v240
	v_mov_b32_e32 v229, 0
	v_lshl_add_u64 v[224:225], v[228:229], 0, v[224:225]
	s_waitcnt vmcnt(8)
; DI float silu_fast(float x) { return x * __builtin_amdgcn_rcpf(1.f + __expf(-x)); }
; template <int CTRL> DI float dppf(float v) { return __builtin_bit_cast(float, __builtin_amdgcn_update_dpp(0, __builtin_bit_cast(int, v), CTRL, 0xf, 0xf, true)); }
; DI void Epi::fused(const f32x4 (&acc)[2][2][4][2], int pm, int pn, int wr, int wc, int fr, int fq) const {
;     ...
;     for (int bj = 0; bj < 2; ++bj) {
;         const int ncol = pn * 256 + bj * 128 + wc * 32 + 8 * fq, j0 = (ncol >> 3) * 4;
;         const f32x4 wa0 = *(const f32x4*)(E.cf0 + j0), wa1 = *(const f32x4*)(E.cf0 + FF2 + j0), wa2 = *(const f32x4*)(E.cf0 + 2 * FF2 + j0);
;         const f32x4 wb0 = *(const f32x4*)(E.cf0 + FFH + j0), wb1 = *(const f32x4*)(E.cf0 + FF2 + FFH + j0), wb2 = *(const f32x4*)(E.cf0 + 2 * FF2 + FFH + j0);
;         const f32x4 ba = *(const f32x4*)(E.cf1 + j0), bb = *(const f32x4*)(E.cf1 + FFH + j0);
; #pragma unroll
;         for (int ai = 0; ai < 2; ++ai) {
;             f32x4 pa = (f32x4){0.f, 0.f, 0.f, 0.f}, pb = pa;
; #pragma unroll
;             for (int m = 0; m < 4; ++m) {
;                 const f32x4 ca = acc[ai][bj][m][0], cb = acc[ai][bj][m][1];
;                 const int row = pm * 256 + ai * 128 + wr * 64 + m * 16 + fr;
;                 float o[4];
; #pragma unroll
;                 for (int e = 0; e < 4; ++e) {
;                     const float a1 = dppf<0x111>(ca[e]) + dppf<0x10F>(pa[e]), a2 = dppf<0x112>(ca[e]) + dppf<0x10E>(pa[e]);
;                     const float b1 = dppf<0x111>(cb[e]) + dppf<0x10F>(pb[e]), b2 = dppf<0x112>(cb[e]) + dppf<0x10E>(pb[e]);
;                     const float ya = fmaf(wa0[e], a2, fmaf(wa1[e], a1, fmaf(wa2[e], ca[e], ba[e])));
;                     const float yb = fmaf(wb0[e], b2, fmaf(wb1[e], b1, fmaf(wb2[e], cb[e], bb[e])));
;                     o[e] = silu_fast(ya) * yb; }
;                 if (m > 0 || fr >= 2) { u32x2 w; w.x = pk2(o[0], o[1]); w.y = pk2(o[2], o[3]); *(u32x2*)(E.d0 + (size_t)row * FFH + j0) = w; }
;                 if ((m == 0 && fr < 2) || (m == 3 && fr >= 14)) { float* hb = E.f0 + ((size_t)(row >> 6) * 4 + (m == 0 ? fr : fr - 12)) * FF2 + ncol; *(f32x4*)hb = ca; *(f32x4*)(hb + 4) = cb; }
;                 pa = ca; pb = cb;
	v_fma_f32 v160, v100, v112, v124
	v_fma_f32 v161, v101, v113, v125
	v_fma_f32 v162, v102, v114, v126
	v_fma_f32 v163, v103, v115, v127
	v_fma_f32 v164, v120, v108, v72
	v_fma_f32 v165, v121, v109, v73
	v_fma_f32 v166, v122, v110, v74
	v_fma_f32 v167, v123, v111, v75
	v_fmac_f32_dpp v160, v112, v88 row_shr:1 row_mask:0xf bank_mask:0xf
	v_fmac_f32_dpp v161, v113, v89 row_shr:1 row_mask:0xf bank_mask:0xf
	v_fmac_f32_dpp v162, v114, v90 row_shr:1 row_mask:0xf bank_mask:0xf
	v_fmac_f32_dpp v163, v115, v91 row_shr:1 row_mask:0xf bank_mask:0xf
	v_fmac_f32_dpp v164, v108, v116 row_shr:1 row_mask:0xf bank_mask:0xf
	v_fmac_f32_dpp v165, v109, v117 row_shr:1 row_mask:0xf bank_mask:0xf
	v_fmac_f32_dpp v166, v110, v118 row_shr:1 row_mask:0xf bank_mask:0xf
	v_fmac_f32_dpp v167, v111, v119 row_shr:1 row_mask:0xf bank_mask:0xf
	v_fmac_f32_dpp v160, v112, v84 row_shr:2 row_mask:0xf bank_mask:0xf
	v_fmac_f32_dpp v161, v113, v85 row_shr:2 row_mask:0xf bank_mask:0xf
	v_fmac_f32_dpp v162, v114, v86 row_shr:2 row_mask:0xf bank_mask:0xf
	v_fmac_f32_dpp v163, v115, v87 row_shr:2 row_mask:0xf bank_mask:0xf
	v_fmac_f32_dpp v164, v108, v104 row_shr:2 row_mask:0xf bank_mask:0xf
	v_fmac_f32_dpp v165, v109, v105 row_shr:2 row_mask:0xf bank_mask:0xf
	v_fmac_f32_dpp v166, v110, v106 row_shr:2 row_mask:0xf bank_mask:0xf
	v_fmac_f32_dpp v167, v111, v107 row_shr:2 row_mask:0xf bank_mask:0xf
	v_mul_f32_e32 v168, 0xbfb8aa3b, v160
	v_mul_f32_e32 v169, 0xbfb8aa3b, v161
	v_mul_f32_e32 v170, 0xbfb8aa3b, v162
	v_mul_f32_e32 v171, 0xbfb8aa3b, v163
	v_exp_f32_e32 v168, v168
	v_exp_f32_e32 v169, v169
	v_exp_f32_e32 v170, v170
	v_exp_f32_e32 v171, v171
	v_add_f32_e32 v168, 1.0, v168
	v_add_f32_e32 v169, 1.0, v169
	v_add_f32_e32 v170, 1.0, v170
	v_add_f32_e32 v171, 1.0, v171
	v_rcp_f32_e32 v168, v168
	v_rcp_f32_e32 v169, v169
	v_rcp_f32_e32 v170, v170
	v_rcp_f32_e32 v171, v171
	v_mov_b64_e32 v[174:175], v[224:225]
	v_mul_f32_e32 v160, v160, v168
	v_mul_f32_e32 v161, v161, v169
	v_mul_f32_e32 v162, v162, v170
	v_mul_f32_e32 v163, v163, v171
	v_mul_f32_e32 v160, v164, v160
	v_mul_f32_e32 v161, v165, v161
	v_mul_f32_e32 v162, v166, v162
	v_mul_f32_e32 v163, v167, v163
	v_cvt_pk_bf16_f32 v172, v160, v161
	v_cvt_pk_bf16_f32 v173, v162, v163
	s_and_saveexec_b64 s[76:77], s[38:39]
	global_store_dwordx2 v[174:175], v[172:173], off
	s_or_b64 exec, exec, s[76:77]
	s_ashr_i32 s80, s71, 6
	s_lshl_b32 s80, s80, 2
	v_add_u32_e32 v226, s80, v188
	v_mov_b64_e32 v[174:175], s[8:9]
	s_movk_i32 s80, 0x5800
	v_mad_i64_i32 v[174:175], s[78:79], v226, s80, v[174:175]
	v_lshl_add_u64 v[174:175], v[228:229], 2, v[174:175]
	s_and_saveexec_b64 s[76:77], s[40:41]
	global_store_dwordx4 v[174:175], v[112:115], off
	global_store_dwordx4 v[174:175], v[108:111], off offset:16
	s_or_b64 exec, exec, s[76:77]
	v_fma_f32 v208, v100, v96, v124
	v_fma_f32 v209, v101, v97, v125
	v_fma_f32 v210, v102, v98, v126
	v_fma_f32 v211, v103, v99, v127
	v_fma_f32 v212, v120, v92, v72
	v_fma_f32 v213, v121, v93, v73
	v_fma_f32 v214, v122, v94, v74
	v_fma_f32 v215, v123, v95, v75
	v_fmac_f32_dpp v208, v96, v88 row_shr:1 row_mask:0xf bank_mask:0xf
	v_fmac_f32_dpp v209, v97, v89 row_shr:1 row_mask:0xf bank_mask:0xf
	v_fmac_f32_dpp v210, v98, v90 row_shr:1 row_mask:0xf bank_mask:0xf
	v_fmac_f32_dpp v211, v99, v91 row_shr:1 row_mask:0xf bank_mask:0xf
	v_fmac_f32_dpp v212, v92, v116 row_shr:1 row_mask:0xf bank_mask:0xf
	v_fmac_f32_dpp v213, v93, v117 row_shr:1 row_mask:0xf bank_mask:0xf
	v_fmac_f32_dpp v214, v94, v118 row_shr:1 row_mask:0xf bank_mask:0xf
	v_fmac_f32_dpp v215, v95, v119 row_shr:1 row_mask:0xf bank_mask:0xf
	v_fmac_f32_dpp v208, v112, v88 row_shl:15 row_mask:0xf bank_mask:0xf
	v_fmac_f32_dpp v209, v113, v89 row_shl:15 row_mask:0xf bank_mask:0xf
	v_fmac_f32_dpp v210, v114, v90 row_shl:15 row_mask:0xf bank_mask:0xf
	v_fmac_f32_dpp v211, v115, v91 row_shl:15 row_mask:0xf bank_mask:0xf
	v_fmac_f32_dpp v212, v108, v116 row_shl:15 row_mask:0xf bank_mask:0xf
	v_fmac_f32_dpp v213, v109, v117 row_shl:15 row_mask:0xf bank_mask:0xf
	v_fmac_f32_dpp v214, v110, v118 row_shl:15 row_mask:0xf bank_mask:0xf
	v_fmac_f32_dpp v215, v111, v119 row_shl:15 row_mask:0xf bank_mask:0xf
	v_fmac_f32_dpp v208, v96, v84 row_shr:2 row_mask:0xf bank_mask:0xf
	v_fmac_f32_dpp v209, v97, v85 row_shr:2 row_mask:0xf bank_mask:0xf
	v_fmac_f32_dpp v210, v98, v86 row_shr:2 row_mask:0xf bank_mask:0xf
	v_fmac_f32_dpp v211, v99, v87 row_shr:2 row_mask:0xf bank_mask:0xf
	v_fmac_f32_dpp v212, v92, v104 row_shr:2 row_mask:0xf bank_mask:0xf
	v_fmac_f32_dpp v213, v93, v105 row_shr:2 row_mask:0xf bank_mask:0xf
	v_fmac_f32_dpp v214, v94, v106 row_shr:2 row_mask:0xf bank_mask:0xf
	v_fmac_f32_dpp v215, v95, v107 row_shr:2 row_mask:0xf bank_mask:0xf
	v_fmac_f32_dpp v208, v112, v84 row_shl:14 row_mask:0xf bank_mask:0xf
	v_fmac_f32_dpp v209, v113, v85 row_shl:14 row_mask:0xf bank_mask:0xf
	v_fmac_f32_dpp v210, v114, v86 row_shl:14 row_mask:0xf bank_mask:0xf
	v_fmac_f32_dpp v211, v115, v87 row_shl:14 row_mask:0xf bank_mask:0xf
	v_fmac_f32_dpp v212, v108, v104 row_shl:14 row_mask:0xf bank_mask:0xf
	v_fmac_f32_dpp v213, v109, v105 row_shl:14 row_mask:0xf bank_mask:0xf
	v_fmac_f32_dpp v214, v110, v106 row_shl:14 row_mask:0xf bank_mask:0xf
	v_fmac_f32_dpp v215, v111, v107 row_shl:14 row_mask:0xf bank_mask:0xf
	v_mul_f32_e32 v216, 0xbfb8aa3b, v208
	v_mul_f32_e32 v217, 0xbfb8aa3b, v209
	v_mul_f32_e32 v218, 0xbfb8aa3b, v210
	v_mul_f32_e32 v219, 0xbfb8aa3b, v211
	v_exp_f32_e32 v216, v216
	v_exp_f32_e32 v217, v217
	v_exp_f32_e32 v218, v218
	v_exp_f32_e32 v219, v219
	v_add_f32_e32 v216, 1.0, v216
	v_add_f32_e32 v217, 1.0, v217
	v_add_f32_e32 v218, 1.0, v218
	v_add_f32_e32 v219, 1.0, v219
; DI float silu_fast(float x) { return x * __builtin_amdgcn_rcpf(1.f + __expf(-x)); }
; template <int CTRL> DI float dppf(float v) { return __builtin_bit_cast(float, __builtin_amdgcn_update_dpp(0, __builtin_bit_cast(int, v), CTRL, 0xf, 0xf, true)); }
; DI void Epi::fused(const f32x4 (&acc)[2][2][4][2], int pm, int pn, int wr, int wc, int fr, int fq) const {
;     ...
;     for (int bj = 0; bj < 2; ++bj) {
;         const int ncol = pn * 256 + bj * 128 + wc * 32 + 8 * fq, j0 = (ncol >> 3) * 4;
;         const f32x4 wa0 = *(const f32x4*)(E.cf0 + j0), wa1 = *(const f32x4*)(E.cf0 + FF2 + j0), wa2 = *(const f32x4*)(E.cf0 + 2 * FF2 + j0);
;         const f32x4 wb0 = *(const f32x4*)(E.cf0 + FFH + j0), wb1 = *(const f32x4*)(E.cf0 + FF2 + FFH + j0), wb2 = *(const f32x4*)(E.cf0 + 2 * FF2 + FFH + j0);
;         const f32x4 ba = *(const f32x4*)(E.cf1 + j0), bb = *(const f32x4*)(E.cf1 + FFH + j0);
; #pragma unroll
;         for (int ai = 0; ai < 2; ++ai) {
;             f32x4 pa = (f32x4){0.f, 0.f, 0.f, 0.f}, pb = pa;
; #pragma unroll
;             for (int m = 0; m < 4; ++m) {
;                 const f32x4 ca = acc[ai][bj][m][0], cb = acc[ai][bj][m][1];
;                 const int row = pm * 256 + ai * 128 + wr * 64 + m * 16 + fr;
;                 float o[4];
; #pragma unroll
;                 for (int e = 0; e < 4; ++e) {
;                     const float a1 = dppf<0x111>(ca[e]) + dppf<0x10F>(pa[e]), a2 = dppf<0x112>(ca[e]) + dppf<0x10E>(pa[e]);
;                     const float b1 = dppf<0x111>(cb[e]) + dppf<0x10F>(pb[e]), b2 = dppf<0x112>(cb[e]) + dppf<0x10E>(pb[e]);
;                     const float ya = fmaf(wa0[e], a2, fmaf(wa1[e], a1, fmaf(wa2[e], ca[e], ba[e])));
;                     const float yb = fmaf(wb0[e], b2, fmaf(wb1[e], b1, fmaf(wb2[e], cb[e], bb[e])));
;                     o[e] = silu_fast(ya) * yb; }
;                 if (m > 0 || fr >= 2) { u32x2 w; w.x = pk2(o[0], o[1]); w.y = pk2(o[2], o[3]); *(u32x2*)(E.d0 + (size_t)row * FFH + j0) = w; }
;                 if ((m == 0 && fr < 2) || (m == 3 && fr >= 14)) { float* hb = E.f0 + ((size_t)(row >> 6) * 4 + (m == 0 ? fr : fr - 12)) * FF2 + ncol; *(f32x4*)hb = ca; *(f32x4*)(hb + 4) = cb; }
;                 pa = ca; pb = cb;
	v_rcp_f32_e32 v216, v216
	v_rcp_f32_e32 v217, v217
	v_rcp_f32_e32 v218, v218
	v_rcp_f32_e32 v219, v219
	s_mov_b32 s80, 0x16000
	s_mov_b32 s81, 0
	v_lshl_add_u64 v[222:223], v[224:225], 0, s[80:81]
	v_mul_f32_e32 v208, v208, v216
	v_mul_f32_e32 v209, v209, v217
	v_mul_f32_e32 v210, v210, v218
	v_mul_f32_e32 v211, v211, v219
	v_mul_f32_e32 v208, v212, v208
	v_mul_f32_e32 v209, v213, v209
	v_mul_f32_e32 v210, v214, v210
	v_mul_f32_e32 v211, v215, v211
	v_cvt_pk_bf16_f32 v220, v208, v209
	v_cvt_pk_bf16_f32 v221, v210, v211
	global_store_dwordx2 v[222:223], v[220:221], off
	v_fma_f32 v160, v100, v80, v124
	v_fma_f32 v161, v101, v81, v125
	v_fma_f32 v162, v102, v82, v126
	v_fma_f32 v163, v103, v83, v127
	v_fma_f32 v164, v120, v76, v72
	v_fma_f32 v165, v121, v77, v73
	v_fma_f32 v166, v122, v78, v74
	v_fma_f32 v167, v123, v79, v75
	v_fmac_f32_dpp v160, v80, v88 row_shr:1 row_mask:0xf bank_mask:0xf
	v_fmac_f32_dpp v161, v81, v89 row_shr:1 row_mask:0xf bank_mask:0xf
	v_fmac_f32_dpp v162, v82, v90 row_shr:1 row_mask:0xf bank_mask:0xf
	v_fmac_f32_dpp v163, v83, v91 row_shr:1 row_mask:0xf bank_mask:0xf
	v_fmac_f32_dpp v164, v76, v116 row_shr:1 row_mask:0xf bank_mask:0xf
	v_fmac_f32_dpp v165, v77, v117 row_shr:1 row_mask:0xf bank_mask:0xf
	v_fmac_f32_dpp v166, v78, v118 row_shr:1 row_mask:0xf bank_mask:0xf
	v_fmac_f32_dpp v167, v79, v119 row_shr:1 row_mask:0xf bank_mask:0xf
	v_fmac_f32_dpp v160, v96, v88 row_shl:15 row_mask:0xf bank_mask:0xf
	v_fmac_f32_dpp v161, v97, v89 row_shl:15 row_mask:0xf bank_mask:0xf
	v_fmac_f32_dpp v162, v98, v90 row_shl:15 row_mask:0xf bank_mask:0xf
	v_fmac_f32_dpp v163, v99, v91 row_shl:15 row_mask:0xf bank_mask:0xf
	v_fmac_f32_dpp v164, v92, v116 row_shl:15 row_mask:0xf bank_mask:0xf
	v_fmac_f32_dpp v165, v93, v117 row_shl:15 row_mask:0xf bank_mask:0xf
	v_fmac_f32_dpp v166, v94, v118 row_shl:15 row_mask:0xf bank_mask:0xf
	v_fmac_f32_dpp v167, v95, v119 row_shl:15 row_mask:0xf bank_mask:0xf
	v_fmac_f32_dpp v160, v80, v84 row_shr:2 row_mask:0xf bank_mask:0xf
	v_fmac_f32_dpp v161, v81, v85 row_shr:2 row_mask:0xf bank_mask:0xf
	v_fmac_f32_dpp v162, v82, v86 row_shr:2 row_mask:0xf bank_mask:0xf
	v_fmac_f32_dpp v163, v83, v87 row_shr:2 row_mask:0xf bank_mask:0xf
	v_fmac_f32_dpp v164, v76, v104 row_shr:2 row_mask:0xf bank_mask:0xf
	v_fmac_f32_dpp v165, v77, v105 row_shr:2 row_mask:0xf bank_mask:0xf
	v_fmac_f32_dpp v166, v78, v106 row_shr:2 row_mask:0xf bank_mask:0xf
	v_fmac_f32_dpp v167, v79, v107 row_shr:2 row_mask:0xf bank_mask:0xf
	v_fmac_f32_dpp v160, v96, v84 row_shl:14 row_mask:0xf bank_mask:0xf
	v_fmac_f32_dpp v161, v97, v85 row_shl:14 row_mask:0xf bank_mask:0xf
	v_fmac_f32_dpp v162, v98, v86 row_shl:14 row_mask:0xf bank_mask:0xf
	v_fmac_f32_dpp v163, v99, v87 row_shl:14 row_mask:0xf bank_mask:0xf
	v_fmac_f32_dpp v164, v92, v104 row_shl:14 row_mask:0xf bank_mask:0xf
	v_fmac_f32_dpp v165, v93, v105 row_shl:14 row_mask:0xf bank_mask:0xf
	v_fmac_f32_dpp v166, v94, v106 row_shl:14 row_mask:0xf bank_mask:0xf
	v_fmac_f32_dpp v167, v95, v107 row_shl:14 row_mask:0xf bank_mask:0xf
	v_mul_f32_e32 v168, 0xbfb8aa3b, v160
	v_mul_f32_e32 v169, 0xbfb8aa3b, v161
	v_mul_f32_e32 v170, 0xbfb8aa3b, v162
	v_mul_f32_e32 v171, 0xbfb8aa3b, v163
	v_exp_f32_e32 v168, v168
	v_exp_f32_e32 v169, v169
	v_exp_f32_e32 v170, v170
	v_exp_f32_e32 v171, v171
	v_add_f32_e32 v168, 1.0, v168
	v_add_f32_e32 v169, 1.0, v169
	v_add_f32_e32 v170, 1.0, v170
	v_add_f32_e32 v171, 1.0, v171
	v_rcp_f32_e32 v168, v168
	v_rcp_f32_e32 v169, v169
	v_rcp_f32_e32 v170, v170
	v_rcp_f32_e32 v171, v171
	s_mov_b32 s80, 0x2c000
	s_mov_b32 s81, 0
	v_lshl_add_u64 v[174:175], v[224:225], 0, s[80:81]
	v_mul_f32_e32 v160, v160, v168
	v_mul_f32_e32 v161, v161, v169
	v_mul_f32_e32 v162, v162, v170
	v_mul_f32_e32 v163, v163, v171
	v_mul_f32_e32 v160, v164, v160
	v_mul_f32_e32 v161, v165, v161
	v_mul_f32_e32 v162, v166, v162
	v_mul_f32_e32 v163, v167, v163
	v_cvt_pk_bf16_f32 v172, v160, v161
	v_cvt_pk_bf16_f32 v173, v162, v163
	global_store_dwordx2 v[174:175], v[172:173], off
	v_fma_f32 v208, v100, v68, v124
	v_fma_f32 v209, v101, v69, v125
	v_fma_f32 v210, v102, v70, v126
	v_fma_f32 v211, v103, v71, v127
	v_fma_f32 v212, v120, v64, v72
	v_fma_f32 v213, v121, v65, v73
	v_fma_f32 v214, v122, v66, v74
	v_fma_f32 v215, v123, v67, v75
	v_fmac_f32_dpp v208, v68, v88 row_shr:1 row_mask:0xf bank_mask:0xf
	v_fmac_f32_dpp v209, v69, v89 row_shr:1 row_mask:0xf bank_mask:0xf
	v_fmac_f32_dpp v210, v70, v90 row_shr:1 row_mask:0xf bank_mask:0xf
	v_fmac_f32_dpp v211, v71, v91 row_shr:1 row_mask:0xf bank_mask:0xf
	v_fmac_f32_dpp v212, v64, v116 row_shr:1 row_mask:0xf bank_mask:0xf
	v_fmac_f32_dpp v213, v65, v117 row_shr:1 row_mask:0xf bank_mask:0xf
	v_fmac_f32_dpp v214, v66, v118 row_shr:1 row_mask:0xf bank_mask:0xf
	v_fmac_f32_dpp v215, v67, v119 row_shr:1 row_mask:0xf bank_mask:0xf
	v_fmac_f32_dpp v208, v80, v88 row_shl:15 row_mask:0xf bank_mask:0xf
	v_fmac_f32_dpp v209, v81, v89 row_shl:15 row_mask:0xf bank_mask:0xf
	v_fmac_f32_dpp v210, v82, v90 row_shl:15 row_mask:0xf bank_mask:0xf
	v_fmac_f32_dpp v211, v83, v91 row_shl:15 row_mask:0xf bank_mask:0xf
	v_fmac_f32_dpp v212, v76, v116 row_shl:15 row_mask:0xf bank_mask:0xf
	v_fmac_f32_dpp v213, v77, v117 row_shl:15 row_mask:0xf bank_mask:0xf
	v_fmac_f32_dpp v214, v78, v118 row_shl:15 row_mask:0xf bank_mask:0xf
	v_fmac_f32_dpp v215, v79, v119 row_shl:15 row_mask:0xf bank_mask:0xf
	v_fmac_f32_dpp v208, v68, v84 row_shr:2 row_mask:0xf bank_mask:0xf
	v_fmac_f32_dpp v209, v69, v85 row_shr:2 row_mask:0xf bank_mask:0xf
	v_fmac_f32_dpp v210, v70, v86 row_shr:2 row_mask:0xf bank_mask:0xf
	v_fmac_f32_dpp v211, v71, v87 row_shr:2 row_mask:0xf bank_mask:0xf
; DI float silu_fast(float x) { return x * __builtin_amdgcn_rcpf(1.f + __expf(-x)); }
; template <int CTRL> DI float dppf(float v) { return __builtin_bit_cast(float, __builtin_amdgcn_update_dpp(0, __builtin_bit_cast(int, v), CTRL, 0xf, 0xf, true)); }
; DI void Epi::fused(const f32x4 (&acc)[2][2][4][2], int pm, int pn, int wr, int wc, int fr, int fq) const {
;     ...
;     for (int bj = 0; bj < 2; ++bj) {
;         const int ncol = pn * 256 + bj * 128 + wc * 32 + 8 * fq, j0 = (ncol >> 3) * 4;
;         const f32x4 wa0 = *(const f32x4*)(E.cf0 + j0), wa1 = *(const f32x4*)(E.cf0 + FF2 + j0), wa2 = *(const f32x4*)(E.cf0 + 2 * FF2 + j0);
;         const f32x4 wb0 = *(const f32x4*)(E.cf0 + FFH + j0), wb1 = *(const f32x4*)(E.cf0 + FF2 + FFH + j0), wb2 = *(const f32x4*)(E.cf0 + 2 * FF2 + FFH + j0);
;         const f32x4 ba = *(const f32x4*)(E.cf1 + j0), bb = *(const f32x4*)(E.cf1 + FFH + j0);
; #pragma unroll
;         for (int ai = 0; ai < 2; ++ai) {
;             f32x4 pa = (f32x4){0.f, 0.f, 0.f, 0.f}, pb = pa;
; #pragma unroll
;             for (int m = 0; m < 4; ++m) {
;                 const f32x4 ca = acc[ai][bj][m][0], cb = acc[ai][bj][m][1];
;                 const int row = pm * 256 + ai * 128 + wr * 64 + m * 16 + fr;
;                 float o[4];
; #pragma unroll
;                 for (int e = 0; e < 4; ++e) {
;                     const float a1 = dppf<0x111>(ca[e]) + dppf<0x10F>(pa[e]), a2 = dppf<0x112>(ca[e]) + dppf<0x10E>(pa[e]);
;                     const float b1 = dppf<0x111>(cb[e]) + dppf<0x10F>(pb[e]), b2 = dppf<0x112>(cb[e]) + dppf<0x10E>(pb[e]);
;                     const float ya = fmaf(wa0[e], a2, fmaf(wa1[e], a1, fmaf(wa2[e], ca[e], ba[e])));
;                     const float yb = fmaf(wb0[e], b2, fmaf(wb1[e], b1, fmaf(wb2[e], cb[e], bb[e])));
;                     o[e] = silu_fast(ya) * yb; }
;                 if (m > 0 || fr >= 2) { u32x2 w; w.x = pk2(o[0], o[1]); w.y = pk2(o[2], o[3]); *(u32x2*)(E.d0 + (size_t)row * FFH + j0) = w; }
;                 if ((m == 0 && fr < 2) || (m == 3 && fr >= 14)) { float* hb = E.f0 + ((size_t)(row >> 6) * 4 + (m == 0 ? fr : fr - 12)) * FF2 + ncol; *(f32x4*)hb = ca; *(f32x4*)(hb + 4) = cb; }
;                 pa = ca; pb = cb;
	v_fmac_f32_dpp v212, v64, v104 row_shr:2 row_mask:0xf bank_mask:0xf
	v_fmac_f32_dpp v213, v65, v105 row_shr:2 row_mask:0xf bank_mask:0xf
	v_fmac_f32_dpp v214, v66, v106 row_shr:2 row_mask:0xf bank_mask:0xf
	v_fmac_f32_dpp v215, v67, v107 row_shr:2 row_mask:0xf bank_mask:0xf
	v_fmac_f32_dpp v208, v80, v84 row_shl:14 row_mask:0xf bank_mask:0xf
	v_fmac_f32_dpp v209, v81, v85 row_shl:14 row_mask:0xf bank_mask:0xf
	v_fmac_f32_dpp v210, v82, v86 row_shl:14 row_mask:0xf bank_mask:0xf
	v_fmac_f32_dpp v211, v83, v87 row_shl:14 row_mask:0xf bank_mask:0xf
	v_fmac_f32_dpp v212, v76, v104 row_shl:14 row_mask:0xf bank_mask:0xf
	v_fmac_f32_dpp v213, v77, v105 row_shl:14 row_mask:0xf bank_mask:0xf
	v_fmac_f32_dpp v214, v78, v106 row_shl:14 row_mask:0xf bank_mask:0xf
	v_fmac_f32_dpp v215, v79, v107 row_shl:14 row_mask:0xf bank_mask:0xf
	v_mul_f32_e32 v216, 0xbfb8aa3b, v208
	v_mul_f32_e32 v217, 0xbfb8aa3b, v209
	v_mul_f32_e32 v218, 0xbfb8aa3b, v210
	v_mul_f32_e32 v219, 0xbfb8aa3b, v211
	v_exp_f32_e32 v216, v216
	v_exp_f32_e32 v217, v217
	v_exp_f32_e32 v218, v218
	v_exp_f32_e32 v219, v219
	v_add_f32_e32 v216, 1.0, v216
	v_add_f32_e32 v217, 1.0, v217
	v_add_f32_e32 v218, 1.0, v218
	v_add_f32_e32 v219, 1.0, v219
	v_rcp_f32_e32 v216, v216
	v_rcp_f32_e32 v217, v217
	v_rcp_f32_e32 v218, v218
	v_rcp_f32_e32 v219, v219
	s_mov_b32 s80, 0x42000
	s_mov_b32 s81, 0
	v_lshl_add_u64 v[222:223], v[224:225], 0, s[80:81]
	v_mul_f32_e32 v208, v208, v216
	v_mul_f32_e32 v209, v209, v217
	v_mul_f32_e32 v210, v210, v218
	v_mul_f32_e32 v211, v211, v219
	v_mul_f32_e32 v208, v212, v208
	v_mul_f32_e32 v209, v213, v209
	v_mul_f32_e32 v210, v214, v210
	v_mul_f32_e32 v211, v215, v211
	v_cvt_pk_bf16_f32 v220, v208, v209
	v_cvt_pk_bf16_f32 v221, v210, v211
	global_store_dwordx2 v[222:223], v[220:221], off
	s_ashr_i32 s80, s71, 6
	s_lshl_b32 s80, s80, 2
	v_add_u32_e32 v226, s80, v190
	v_mov_b64_e32 v[222:223], s[8:9]
	s_movk_i32 s80, 0x5800
	v_mad_i64_i32 v[222:223], s[78:79], v226, s80, v[222:223]
	v_lshl_add_u64 v[222:223], v[228:229], 2, v[222:223]
	s_and_saveexec_b64 s[76:77], s[42:43]
	global_store_dwordx4 v[222:223], v[68:71], off
	global_store_dwordx4 v[222:223], v[64:67], off offset:16
	s_or_b64 exec, exec, s[76:77]
	v_add_u32_e32 v228, 128, v199
	v_mov_b64_e32 v[224:225], s[12:13]
	s_movk_i32 s80, 0x1600
	v_mad_i64_i32 v[224:225], s[78:79], v228, s80, v[224:225]
	v_add_u32_e32 v228, 128, v240
	v_mov_b32_e32 v229, 0
	v_lshl_add_u64 v[224:225], v[228:229], 0, v[224:225]
	v_fma_f32 v160, v100, v48, v124
	v_fma_f32 v161, v101, v49, v125
	v_fma_f32 v162, v102, v50, v126
	v_fma_f32 v163, v103, v51, v127
	v_fma_f32 v164, v120, v44, v72
	v_fma_f32 v165, v121, v45, v73
	v_fma_f32 v166, v122, v46, v74
	v_fma_f32 v167, v123, v47, v75
	v_fmac_f32_dpp v160, v48, v88 row_shr:1 row_mask:0xf bank_mask:0xf
	v_fmac_f32_dpp v161, v49, v89 row_shr:1 row_mask:0xf bank_mask:0xf
	v_fmac_f32_dpp v162, v50, v90 row_shr:1 row_mask:0xf bank_mask:0xf
	v_fmac_f32_dpp v163, v51, v91 row_shr:1 row_mask:0xf bank_mask:0xf
	v_fmac_f32_dpp v164, v44, v116 row_shr:1 row_mask:0xf bank_mask:0xf
	v_fmac_f32_dpp v165, v45, v117 row_shr:1 row_mask:0xf bank_mask:0xf
	v_fmac_f32_dpp v166, v46, v118 row_shr:1 row_mask:0xf bank_mask:0xf
	v_fmac_f32_dpp v167, v47, v119 row_shr:1 row_mask:0xf bank_mask:0xf
	v_fmac_f32_dpp v160, v48, v84 row_shr:2 row_mask:0xf bank_mask:0xf
	v_fmac_f32_dpp v161, v49, v85 row_shr:2 row_mask:0xf bank_mask:0xf
	v_fmac_f32_dpp v162, v50, v86 row_shr:2 row_mask:0xf bank_mask:0xf
	v_fmac_f32_dpp v163, v51, v87 row_shr:2 row_mask:0xf bank_mask:0xf
	v_fmac_f32_dpp v164, v44, v104 row_shr:2 row_mask:0xf bank_mask:0xf
	v_fmac_f32_dpp v165, v45, v105 row_shr:2 row_mask:0xf bank_mask:0xf
	v_fmac_f32_dpp v166, v46, v106 row_shr:2 row_mask:0xf bank_mask:0xf
	v_fmac_f32_dpp v167, v47, v107 row_shr:2 row_mask:0xf bank_mask:0xf
	v_mul_f32_e32 v168, 0xbfb8aa3b, v160
	v_mul_f32_e32 v169, 0xbfb8aa3b, v161
	v_mul_f32_e32 v170, 0xbfb8aa3b, v162
	v_mul_f32_e32 v171, 0xbfb8aa3b, v163
	v_exp_f32_e32 v168, v168
	v_exp_f32_e32 v169, v169
	v_exp_f32_e32 v170, v170
	v_exp_f32_e32 v171, v171
	v_add_f32_e32 v168, 1.0, v168
	v_add_f32_e32 v169, 1.0, v169
	v_add_f32_e32 v170, 1.0, v170
	v_add_f32_e32 v171, 1.0, v171
	v_rcp_f32_e32 v168, v168
	v_rcp_f32_e32 v169, v169
	v_rcp_f32_e32 v170, v170
	v_rcp_f32_e32 v171, v171
	v_mov_b64_e32 v[174:175], v[224:225]
	v_mul_f32_e32 v160, v160, v168
	v_mul_f32_e32 v161, v161, v169
	v_mul_f32_e32 v162, v162, v170
	v_mul_f32_e32 v163, v163, v171
	v_mul_f32_e32 v160, v164, v160
	v_mul_f32_e32 v161, v165, v161
	v_mul_f32_e32 v162, v166, v162
	v_mul_f32_e32 v163, v167, v163
	v_cvt_pk_bf16_f32 v172, v160, v161
	v_cvt_pk_bf16_f32 v173, v162, v163
	s_and_saveexec_b64 s[76:77], s[38:39]
	global_store_dwordx2 v[174:175], v[172:173], off
	s_or_b64 exec, exec, s[76:77]
	s_ashr_i32 s80, s71, 6
	s_lshl_b32 s80, s80, 2
	s_add_i32 s80, s80, 8
	v_add_u32_e32 v226, s80, v188
	v_mov_b64_e32 v[174:175], s[8:9]
	s_movk_i32 s80, 0x5800
	v_mad_i64_i32 v[174:175], s[78:79], v226, s80, v[174:175]
	v_lshl_add_u64 v[174:175], v[228:229], 2, v[174:175]
	s_and_saveexec_b64 s[76:77], s[40:41]
	global_store_dwordx4 v[174:175], v[48:51], off
	global_store_dwordx4 v[174:175], v[44:47], off offset:16
	s_or_b64 exec, exec, s[76:77]
	v_fma_f32 v208, v100, v24, v124
	v_fma_f32 v209, v101, v25, v125
	v_fma_f32 v210, v102, v26, v126
	v_fma_f32 v211, v103, v27, v127
	v_fma_f32 v212, v120, v20, v72
	v_fma_f32 v213, v121, v21, v73
	v_fma_f32 v214, v122, v22, v74
	v_fma_f32 v215, v123, v23, v75
	v_fmac_f32_dpp v208, v24, v88 row_shr:1 row_mask:0xf bank_mask:0xf
	v_fmac_f32_dpp v209, v25, v89 row_shr:1 row_mask:0xf bank_mask:0xf
; DI float silu_fast(float x) { return x * __builtin_amdgcn_rcpf(1.f + __expf(-x)); }
; template <int CTRL> DI float dppf(float v) { return __builtin_bit_cast(float, __builtin_amdgcn_update_dpp(0, __builtin_bit_cast(int, v), CTRL, 0xf, 0xf, true)); }
; DI void Epi::fused(const f32x4 (&acc)[2][2][4][2], int pm, int pn, int wr, int wc, int fr, int fq) const {
;     ...
;     for (int bj = 0; bj < 2; ++bj) {
;         const int ncol = pn * 256 + bj * 128 + wc * 32 + 8 * fq, j0 = (ncol >> 3) * 4;
;         const f32x4 wa0 = *(const f32x4*)(E.cf0 + j0), wa1 = *(const f32x4*)(E.cf0 + FF2 + j0), wa2 = *(const f32x4*)(E.cf0 + 2 * FF2 + j0);
;         const f32x4 wb0 = *(const f32x4*)(E.cf0 + FFH + j0), wb1 = *(const f32x4*)(E.cf0 + FF2 + FFH + j0), wb2 = *(const f32x4*)(E.cf0 + 2 * FF2 + FFH + j0);
;         const f32x4 ba = *(const f32x4*)(E.cf1 + j0), bb = *(const f32x4*)(E.cf1 + FFH + j0);
; #pragma unroll
;         for (int ai = 0; ai < 2; ++ai) {
;             f32x4 pa = (f32x4){0.f, 0.f, 0.f, 0.f}, pb = pa;
; #pragma unroll
;             for (int m = 0; m < 4; ++m) {
;                 const f32x4 ca = acc[ai][bj][m][0], cb = acc[ai][bj][m][1];
;                 const int row = pm * 256 + ai * 128 + wr * 64 + m * 16 + fr;
;                 float o[4];
; #pragma unroll
;                 for (int e = 0; e < 4; ++e) {
;                     const float a1 = dppf<0x111>(ca[e]) + dppf<0x10F>(pa[e]), a2 = dppf<0x112>(ca[e]) + dppf<0x10E>(pa[e]);
;                     const float b1 = dppf<0x111>(cb[e]) + dppf<0x10F>(pb[e]), b2 = dppf<0x112>(cb[e]) + dppf<0x10E>(pb[e]);
;                     const float ya = fmaf(wa0[e], a2, fmaf(wa1[e], a1, fmaf(wa2[e], ca[e], ba[e])));
;                     const float yb = fmaf(wb0[e], b2, fmaf(wb1[e], b1, fmaf(wb2[e], cb[e], bb[e])));
;                     o[e] = silu_fast(ya) * yb; }
;                 if (m > 0 || fr >= 2) { u32x2 w; w.x = pk2(o[0], o[1]); w.y = pk2(o[2], o[3]); *(u32x2*)(E.d0 + (size_t)row * FFH + j0) = w; }
;                 if ((m == 0 && fr < 2) || (m == 3 && fr >= 14)) { float* hb = E.f0 + ((size_t)(row >> 6) * 4 + (m == 0 ? fr : fr - 12)) * FF2 + ncol; *(f32x4*)hb = ca; *(f32x4*)(hb + 4) = cb; }
;                 pa = ca; pb = cb;
	v_fmac_f32_dpp v210, v26, v90 row_shr:1 row_mask:0xf bank_mask:0xf
	v_fmac_f32_dpp v211, v27, v91 row_shr:1 row_mask:0xf bank_mask:0xf
	v_fmac_f32_dpp v212, v20, v116 row_shr:1 row_mask:0xf bank_mask:0xf
	v_fmac_f32_dpp v213, v21, v117 row_shr:1 row_mask:0xf bank_mask:0xf
	v_fmac_f32_dpp v214, v22, v118 row_shr:1 row_mask:0xf bank_mask:0xf
	v_fmac_f32_dpp v215, v23, v119 row_shr:1 row_mask:0xf bank_mask:0xf
	v_fmac_f32_dpp v208, v48, v88 row_shl:15 row_mask:0xf bank_mask:0xf
	v_fmac_f32_dpp v209, v49, v89 row_shl:15 row_mask:0xf bank_mask:0xf
	v_fmac_f32_dpp v210, v50, v90 row_shl:15 row_mask:0xf bank_mask:0xf
	v_fmac_f32_dpp v211, v51, v91 row_shl:15 row_mask:0xf bank_mask:0xf
	v_fmac_f32_dpp v212, v44, v116 row_shl:15 row_mask:0xf bank_mask:0xf
	v_fmac_f32_dpp v213, v45, v117 row_shl:15 row_mask:0xf bank_mask:0xf
	v_fmac_f32_dpp v214, v46, v118 row_shl:15 row_mask:0xf bank_mask:0xf
	v_fmac_f32_dpp v215, v47, v119 row_shl:15 row_mask:0xf bank_mask:0xf
	v_fmac_f32_dpp v208, v24, v84 row_shr:2 row_mask:0xf bank_mask:0xf
	v_fmac_f32_dpp v209, v25, v85 row_shr:2 row_mask:0xf bank_mask:0xf
	v_fmac_f32_dpp v210, v26, v86 row_shr:2 row_mask:0xf bank_mask:0xf
	v_fmac_f32_dpp v211, v27, v87 row_shr:2 row_mask:0xf bank_mask:0xf
	v_fmac_f32_dpp v212, v20, v104 row_shr:2 row_mask:0xf bank_mask:0xf
	v_fmac_f32_dpp v213, v21, v105 row_shr:2 row_mask:0xf bank_mask:0xf
	v_fmac_f32_dpp v214, v22, v106 row_shr:2 row_mask:0xf bank_mask:0xf
	v_fmac_f32_dpp v215, v23, v107 row_shr:2 row_mask:0xf bank_mask:0xf
	v_fmac_f32_dpp v208, v48, v84 row_shl:14 row_mask:0xf bank_mask:0xf
	v_fmac_f32_dpp v209, v49, v85 row_shl:14 row_mask:0xf bank_mask:0xf
	v_fmac_f32_dpp v210, v50, v86 row_shl:14 row_mask:0xf bank_mask:0xf
	v_fmac_f32_dpp v211, v51, v87 row_shl:14 row_mask:0xf bank_mask:0xf
	v_fmac_f32_dpp v212, v44, v104 row_shl:14 row_mask:0xf bank_mask:0xf
	v_fmac_f32_dpp v213, v45, v105 row_shl:14 row_mask:0xf bank_mask:0xf
	v_fmac_f32_dpp v214, v46, v106 row_shl:14 row_mask:0xf bank_mask:0xf
	v_fmac_f32_dpp v215, v47, v107 row_shl:14 row_mask:0xf bank_mask:0xf
	v_mul_f32_e32 v216, 0xbfb8aa3b, v208
	v_mul_f32_e32 v217, 0xbfb8aa3b, v209
	v_mul_f32_e32 v218, 0xbfb8aa3b, v210
	v_mul_f32_e32 v219, 0xbfb8aa3b, v211
	v_exp_f32_e32 v216, v216
	v_exp_f32_e32 v217, v217
	v_exp_f32_e32 v218, v218
	v_exp_f32_e32 v219, v219
	v_add_f32_e32 v216, 1.0, v216
	v_add_f32_e32 v217, 1.0, v217
	v_add_f32_e32 v218, 1.0, v218
	v_add_f32_e32 v219, 1.0, v219
	v_rcp_f32_e32 v216, v216
	v_rcp_f32_e32 v217, v217
	v_rcp_f32_e32 v218, v218
	v_rcp_f32_e32 v219, v219
	s_mov_b32 s80, 0x16000
	s_mov_b32 s81, 0
	v_lshl_add_u64 v[222:223], v[224:225], 0, s[80:81]
	v_mul_f32_e32 v208, v208, v216
	v_mul_f32_e32 v209, v209, v217
	v_mul_f32_e32 v210, v210, v218
	v_mul_f32_e32 v211, v211, v219
	v_mul_f32_e32 v208, v212, v208
	v_mul_f32_e32 v209, v213, v209
	v_mul_f32_e32 v210, v214, v210
	v_mul_f32_e32 v211, v215, v211
	v_cvt_pk_bf16_f32 v220, v208, v209
	v_cvt_pk_bf16_f32 v221, v210, v211
	global_store_dwordx2 v[222:223], v[220:221], off
	v_fma_f32 v160, v100, v28, v124
	v_fma_f32 v161, v101, v29, v125
	v_fma_f32 v162, v102, v30, v126
	v_fma_f32 v163, v103, v31, v127
	v_fma_f32 v164, v120, v32, v72
	v_fma_f32 v165, v121, v33, v73
	v_fma_f32 v166, v122, v34, v74
	v_fma_f32 v167, v123, v35, v75
	v_fmac_f32_dpp v160, v28, v88 row_shr:1 row_mask:0xf bank_mask:0xf
	v_fmac_f32_dpp v161, v29, v89 row_shr:1 row_mask:0xf bank_mask:0xf
	v_fmac_f32_dpp v162, v30, v90 row_shr:1 row_mask:0xf bank_mask:0xf
	v_fmac_f32_dpp v163, v31, v91 row_shr:1 row_mask:0xf bank_mask:0xf
	v_fmac_f32_dpp v164, v32, v116 row_shr:1 row_mask:0xf bank_mask:0xf
	v_fmac_f32_dpp v165, v33, v117 row_shr:1 row_mask:0xf bank_mask:0xf
	v_fmac_f32_dpp v166, v34, v118 row_shr:1 row_mask:0xf bank_mask:0xf
	v_fmac_f32_dpp v167, v35, v119 row_shr:1 row_mask:0xf bank_mask:0xf
	v_fmac_f32_dpp v160, v24, v88 row_shl:15 row_mask:0xf bank_mask:0xf
	v_fmac_f32_dpp v161, v25, v89 row_shl:15 row_mask:0xf bank_mask:0xf
	v_fmac_f32_dpp v162, v26, v90 row_shl:15 row_mask:0xf bank_mask:0xf
	v_fmac_f32_dpp v163, v27, v91 row_shl:15 row_mask:0xf bank_mask:0xf
	v_fmac_f32_dpp v164, v20, v116 row_shl:15 row_mask:0xf bank_mask:0xf
	v_fmac_f32_dpp v165, v21, v117 row_shl:15 row_mask:0xf bank_mask:0xf
	v_fmac_f32_dpp v166, v22, v118 row_shl:15 row_mask:0xf bank_mask:0xf
	v_fmac_f32_dpp v167, v23, v119 row_shl:15 row_mask:0xf bank_mask:0xf
	v_fmac_f32_dpp v160, v28, v84 row_shr:2 row_mask:0xf bank_mask:0xf
	v_fmac_f32_dpp v161, v29, v85 row_shr:2 row_mask:0xf bank_mask:0xf
	v_fmac_f32_dpp v162, v30, v86 row_shr:2 row_mask:0xf bank_mask:0xf
	v_fmac_f32_dpp v163, v31, v87 row_shr:2 row_mask:0xf bank_mask:0xf
	v_fmac_f32_dpp v164, v32, v104 row_shr:2 row_mask:0xf bank_mask:0xf
	v_fmac_f32_dpp v165, v33, v105 row_shr:2 row_mask:0xf bank_mask:0xf
	v_fmac_f32_dpp v166, v34, v106 row_shr:2 row_mask:0xf bank_mask:0xf
	v_fmac_f32_dpp v167, v35, v107 row_shr:2 row_mask:0xf bank_mask:0xf
	v_fmac_f32_dpp v160, v24, v84 row_shl:14 row_mask:0xf bank_mask:0xf
	v_fmac_f32_dpp v161, v25, v85 row_shl:14 row_mask:0xf bank_mask:0xf
	v_fmac_f32_dpp v162, v26, v86 row_shl:14 row_mask:0xf bank_mask:0xf
; DI float silu_fast(float x) { return x * __builtin_amdgcn_rcpf(1.f + __expf(-x)); }
; template <int CTRL> DI float dppf(float v) { return __builtin_bit_cast(float, __builtin_amdgcn_update_dpp(0, __builtin_bit_cast(int, v), CTRL, 0xf, 0xf, true)); }
; DI void Epi::fused(const f32x4 (&acc)[2][2][4][2], int pm, int pn, int wr, int wc, int fr, int fq) const {
;     ...
;     for (int bj = 0; bj < 2; ++bj) {
;         const int ncol = pn * 256 + bj * 128 + wc * 32 + 8 * fq, j0 = (ncol >> 3) * 4;
;         const f32x4 wa0 = *(const f32x4*)(E.cf0 + j0), wa1 = *(const f32x4*)(E.cf0 + FF2 + j0), wa2 = *(const f32x4*)(E.cf0 + 2 * FF2 + j0);
;         const f32x4 wb0 = *(const f32x4*)(E.cf0 + FFH + j0), wb1 = *(const f32x4*)(E.cf0 + FF2 + FFH + j0), wb2 = *(const f32x4*)(E.cf0 + 2 * FF2 + FFH + j0);
;         const f32x4 ba = *(const f32x4*)(E.cf1 + j0), bb = *(const f32x4*)(E.cf1 + FFH + j0);
; #pragma unroll
;         for (int ai = 0; ai < 2; ++ai) {
;             f32x4 pa = (f32x4){0.f, 0.f, 0.f, 0.f}, pb = pa;
; #pragma unroll
;             for (int m = 0; m < 4; ++m) {
;                 const f32x4 ca = acc[ai][bj][m][0], cb = acc[ai][bj][m][1];
;                 const int row = pm * 256 + ai * 128 + wr * 64 + m * 16 + fr;
;                 float o[4];
; #pragma unroll
;                 for (int e = 0; e < 4; ++e) {
;                     const float a1 = dppf<0x111>(ca[e]) + dppf<0x10F>(pa[e]), a2 = dppf<0x112>(ca[e]) + dppf<0x10E>(pa[e]);
;                     const float b1 = dppf<0x111>(cb[e]) + dppf<0x10F>(pb[e]), b2 = dppf<0x112>(cb[e]) + dppf<0x10E>(pb[e]);
;                     const float ya = fmaf(wa0[e], a2, fmaf(wa1[e], a1, fmaf(wa2[e], ca[e], ba[e])));
;                     const float yb = fmaf(wb0[e], b2, fmaf(wb1[e], b1, fmaf(wb2[e], cb[e], bb[e])));
;                     o[e] = silu_fast(ya) * yb; }
;                 if (m > 0 || fr >= 2) { u32x2 w; w.x = pk2(o[0], o[1]); w.y = pk2(o[2], o[3]); *(u32x2*)(E.d0 + (size_t)row * FFH + j0) = w; }
;                 if ((m == 0 && fr < 2) || (m == 3 && fr >= 14)) { float* hb = E.f0 + ((size_t)(row >> 6) * 4 + (m == 0 ? fr : fr - 12)) * FF2 + ncol; *(f32x4*)hb = ca; *(f32x4*)(hb + 4) = cb; }
;                 pa = ca; pb = cb;
	v_fmac_f32_dpp v163, v27, v87 row_shl:14 row_mask:0xf bank_mask:0xf
	v_fmac_f32_dpp v164, v20, v104 row_shl:14 row_mask:0xf bank_mask:0xf
	v_fmac_f32_dpp v165, v21, v105 row_shl:14 row_mask:0xf bank_mask:0xf
	v_fmac_f32_dpp v166, v22, v106 row_shl:14 row_mask:0xf bank_mask:0xf
	v_fmac_f32_dpp v167, v23, v107 row_shl:14 row_mask:0xf bank_mask:0xf
	v_mul_f32_e32 v168, 0xbfb8aa3b, v160
	v_mul_f32_e32 v169, 0xbfb8aa3b, v161
	v_mul_f32_e32 v170, 0xbfb8aa3b, v162
	v_mul_f32_e32 v171, 0xbfb8aa3b, v163
	v_exp_f32_e32 v168, v168
	v_exp_f32_e32 v169, v169
	v_exp_f32_e32 v170, v170
	v_exp_f32_e32 v171, v171
	v_add_f32_e32 v168, 1.0, v168
	v_add_f32_e32 v169, 1.0, v169
	v_add_f32_e32 v170, 1.0, v170
	v_add_f32_e32 v171, 1.0, v171
	v_rcp_f32_e32 v168, v168
	v_rcp_f32_e32 v169, v169
	v_rcp_f32_e32 v170, v170
	v_rcp_f32_e32 v171, v171
	s_mov_b32 s80, 0x2c000
	s_mov_b32 s81, 0
	v_lshl_add_u64 v[174:175], v[224:225], 0, s[80:81]
	v_mul_f32_e32 v160, v160, v168
	v_mul_f32_e32 v161, v161, v169
	v_mul_f32_e32 v162, v162, v170
	v_mul_f32_e32 v163, v163, v171
	v_mul_f32_e32 v160, v164, v160
	v_mul_f32_e32 v161, v165, v161
	v_mul_f32_e32 v162, v166, v162
	v_mul_f32_e32 v163, v167, v163
	v_cvt_pk_bf16_f32 v172, v160, v161
	v_cvt_pk_bf16_f32 v173, v162, v163
	global_store_dwordx2 v[174:175], v[172:173], off
	v_fma_f32 v208, v100, v8, v124
	v_fma_f32 v209, v101, v9, v125
	v_fma_f32 v210, v102, v10, v126
	v_fma_f32 v211, v103, v11, v127
	v_fma_f32 v212, v120, v4, v72
	v_fma_f32 v213, v121, v5, v73
	v_fma_f32 v214, v122, v6, v74
	v_fma_f32 v215, v123, v7, v75
	v_fmac_f32_dpp v208, v8, v88 row_shr:1 row_mask:0xf bank_mask:0xf
	v_fmac_f32_dpp v209, v9, v89 row_shr:1 row_mask:0xf bank_mask:0xf
	v_fmac_f32_dpp v210, v10, v90 row_shr:1 row_mask:0xf bank_mask:0xf
	v_fmac_f32_dpp v211, v11, v91 row_shr:1 row_mask:0xf bank_mask:0xf
	v_fmac_f32_dpp v212, v4, v116 row_shr:1 row_mask:0xf bank_mask:0xf
	v_fmac_f32_dpp v213, v5, v117 row_shr:1 row_mask:0xf bank_mask:0xf
	v_fmac_f32_dpp v214, v6, v118 row_shr:1 row_mask:0xf bank_mask:0xf
	v_fmac_f32_dpp v215, v7, v119 row_shr:1 row_mask:0xf bank_mask:0xf
	v_fmac_f32_dpp v208, v28, v88 row_shl:15 row_mask:0xf bank_mask:0xf
	v_fmac_f32_dpp v209, v29, v89 row_shl:15 row_mask:0xf bank_mask:0xf
	v_fmac_f32_dpp v210, v30, v90 row_shl:15 row_mask:0xf bank_mask:0xf
	v_fmac_f32_dpp v211, v31, v91 row_shl:15 row_mask:0xf bank_mask:0xf
	v_fmac_f32_dpp v212, v32, v116 row_shl:15 row_mask:0xf bank_mask:0xf
	v_fmac_f32_dpp v213, v33, v117 row_shl:15 row_mask:0xf bank_mask:0xf
	v_fmac_f32_dpp v214, v34, v118 row_shl:15 row_mask:0xf bank_mask:0xf
	v_fmac_f32_dpp v215, v35, v119 row_shl:15 row_mask:0xf bank_mask:0xf
	v_fmac_f32_dpp v208, v8, v84 row_shr:2 row_mask:0xf bank_mask:0xf
	v_fmac_f32_dpp v209, v9, v85 row_shr:2 row_mask:0xf bank_mask:0xf
	v_fmac_f32_dpp v210, v10, v86 row_shr:2 row_mask:0xf bank_mask:0xf
	v_fmac_f32_dpp v211, v11, v87 row_shr:2 row_mask:0xf bank_mask:0xf
	v_fmac_f32_dpp v212, v4, v104 row_shr:2 row_mask:0xf bank_mask:0xf
	v_fmac_f32_dpp v213, v5, v105 row_shr:2 row_mask:0xf bank_mask:0xf
	v_fmac_f32_dpp v214, v6, v106 row_shr:2 row_mask:0xf bank_mask:0xf
	v_fmac_f32_dpp v215, v7, v107 row_shr:2 row_mask:0xf bank_mask:0xf
	v_fmac_f32_dpp v208, v28, v84 row_shl:14 row_mask:0xf bank_mask:0xf
	v_fmac_f32_dpp v209, v29, v85 row_shl:14 row_mask:0xf bank_mask:0xf
	v_fmac_f32_dpp v210, v30, v86 row_shl:14 row_mask:0xf bank_mask:0xf
	v_fmac_f32_dpp v211, v31, v87 row_shl:14 row_mask:0xf bank_mask:0xf
	v_fmac_f32_dpp v212, v32, v104 row_shl:14 row_mask:0xf bank_mask:0xf
	v_fmac_f32_dpp v213, v33, v105 row_shl:14 row_mask:0xf bank_mask:0xf
	v_fmac_f32_dpp v214, v34, v106 row_shl:14 row_mask:0xf bank_mask:0xf
	v_fmac_f32_dpp v215, v35, v107 row_shl:14 row_mask:0xf bank_mask:0xf
	v_mul_f32_e32 v216, 0xbfb8aa3b, v208
	v_mul_f32_e32 v217, 0xbfb8aa3b, v209
	v_mul_f32_e32 v218, 0xbfb8aa3b, v210
	v_mul_f32_e32 v219, 0xbfb8aa3b, v211
	v_exp_f32_e32 v216, v216
	v_exp_f32_e32 v217, v217
	v_exp_f32_e32 v218, v218
	v_exp_f32_e32 v219, v219
	v_add_f32_e32 v216, 1.0, v216
	v_add_f32_e32 v217, 1.0, v217
	v_add_f32_e32 v218, 1.0, v218
	v_add_f32_e32 v219, 1.0, v219
	v_rcp_f32_e32 v216, v216
	v_rcp_f32_e32 v217, v217
	v_rcp_f32_e32 v218, v218
	v_rcp_f32_e32 v219, v219
	s_mov_b32 s80, 0x42000
	s_mov_b32 s81, 0
	v_lshl_add_u64 v[222:223], v[224:225], 0, s[80:81]
	v_mul_f32_e32 v208, v208, v216
	v_mul_f32_e32 v209, v209, v217
	v_mul_f32_e32 v210, v210, v218
	v_mul_f32_e32 v211, v211, v219
	v_mul_f32_e32 v208, v212, v208
	v_mul_f32_e32 v209, v213, v209
	v_mul_f32_e32 v210, v214, v210
	v_mul_f32_e32 v211, v215, v211
	v_cvt_pk_bf16_f32 v220, v208, v209
	v_cvt_pk_bf16_f32 v221, v210, v211
	global_store_dwordx2 v[222:223], v[220:221], off
	s_ashr_i32 s80, s71, 6
	s_lshl_b32 s80, s80, 2
	s_add_i32 s80, s80, 8
	v_add_u32_e32 v226, s80, v190
	v_mov_b64_e32 v[222:223], s[8:9]
	s_movk_i32 s80, 0x5800
	v_mad_i64_i32 v[222:223], s[78:79], v226, s80, v[222:223]
	v_lshl_add_u64 v[222:223], v[228:229], 2, v[222:223]
	s_and_saveexec_b64 s[76:77], s[42:43]
	global_store_dwordx4 v[222:223], v[8:11], off
	global_store_dwordx4 v[222:223], v[4:7], off offset:16
	s_or_b64 exec, exec, s[76:77]

; __global__ void __launch_bounds__(512, 2) mega(P p, int ph_lo, int ph_hi, unsigned ph_mask) {
	.amdhsa_kernel _Z4mega1Piij
		.amdhsa_group_segment_fixed_size 0
		.amdhsa_private_segment_fixed_size 0
		.amdhsa_kernarg_size 560
		.amdhsa_user_sgpr_count 2
		.amdhsa_user_sgpr_dispatch_ptr 0
		.amdhsa_user_sgpr_queue_ptr 0
		.amdhsa_user_sgpr_kernarg_segment_ptr 1
		.amdhsa_user_sgpr_dispatch_id 0
		.amdhsa_user_sgpr_kernarg_preload_length 0
		.amdhsa_user_sgpr_kernarg_preload_offset 0
		.amdhsa_user_sgpr_private_segment_size 0
		.amdhsa_uses_dynamic_stack 0
		.amdhsa_enable_private_segment 0
		.amdhsa_system_sgpr_workgroup_id_x 1
		.amdhsa_system_sgpr_workgroup_id_y 0
		.amdhsa_system_sgpr_workgroup_id_z 0
		.amdhsa_system_sgpr_workgroup_info 0
		.amdhsa_system_vgpr_workitem_id 2
		.amdhsa_next_free_vgpr 256
		.amdhsa_next_free_sgpr 102
		.amdhsa_accum_offset 256
		.amdhsa_reserve_vcc 1
		.amdhsa_float_round_mode_32 0
		.amdhsa_float_round_mode_16_64 0
		.amdhsa_float_denorm_mode_32 3
		.amdhsa_float_denorm_mode_16_64 3
		.amdhsa_dx10_clamp 1
		.amdhsa_ieee_mode 1
		.amdhsa_fp16_overflow 0
		.amdhsa_tg_split 0
		.amdhsa_exception_fp_ieee_invalid_op 0
		.amdhsa_exception_fp_denorm_src 0
		.amdhsa_exception_fp_ieee_div_zero 0
		.amdhsa_exception_fp_ieee_overflow 0
		.amdhsa_exception_fp_ieee_underflow 0
		.amdhsa_exception_fp_ieee_inexact 0
		.amdhsa_exception_int_div_zero 0
	.end_amdhsa_kernel

; __global__ void __launch_bounds__(512, 2) mega(P p, int ph_lo, int ph_hi, unsigned ph_mask) {
amdhsa.kernels:
  - .agpr_count:     0
    .args:
      - .offset:         0
        .size:           288
        .value_kind:     by_value
      - .offset:         288
        .size:           4
        .value_kind:     by_value
      - .offset:         292
        .size:           4
        .value_kind:     by_value
      - .offset:         296
        .size:           4
        .value_kind:     by_value
      - .offset:         304
        .size:           4
        .value_kind:     hidden_block_count_x
      - .offset:         308
        .size:           4
        .value_kind:     hidden_block_count_y
      - .offset:         312
        .size:           4
        .value_kind:     hidden_block_count_z
      - .offset:         316
        .size:           2
        .value_kind:     hidden_group_size_x
      - .offset:         318
        .size:           2
        .value_kind:     hidden_group_size_y
      - .offset:         320
        .size:           2
        .value_kind:     hidden_group_size_z
      - .offset:         322
        .size:           2
        .value_kind:     hidden_remainder_x
      - .offset:         324
        .size:           2
        .value_kind:     hidden_remainder_y
      - .offset:         326
        .size:           2
        .value_kind:     hidden_remainder_z
      - .offset:         344
        .size:           8
        .value_kind:     hidden_global_offset_x
      - .offset:         352
        .size:           8
        .value_kind:     hidden_global_offset_y
      - .offset:         360
        .size:           8
        .value_kind:     hidden_global_offset_z
      - .offset:         368
        .size:           2
        .value_kind:     hidden_grid_dims
      - .offset:         392
        .size:           8
        .value_kind:     hidden_multigrid_sync_arg
      - .offset:         424
        .size:           4
        .value_kind:     hidden_dynamic_lds_size
    .group_segment_fixed_size: 0
    .kernarg_segment_align: 8
    .kernarg_segment_size: 560
    .language:       OpenCL C
    .language_version:
      - 2
      - 0
    .max_flat_workgroup_size: 512
    .name:           _Z4mega1Piij
    .private_segment_fixed_size: 0
    .sgpr_count:     108
    .sgpr_spill_count: 391
    .symbol:         _Z4mega1Piij.kd
    .uniform_work_group_size: 1
    .uses_dynamic_stack: false
    .vgpr_count:     256
    .vgpr_spill_count: 0
    .wavefront_size: 64
